# speedup vs baseline: 1.0164x; 1.0164x over previous
; __device__ __forceinline__ int v_st(int k, int c) { const int kk = (k & ~0xC) | ((k & 4) << 1) | ((k & 8) >> 1); return ((kk >> 3) * 4 + (c >> 5)) * 512 + ((kk & 7) * 32 + (c & 31)) * 2; }
; __device__ __forceinline__ int v_rd_base(int lane) { return ((lane & 3) << 3) | (((lane >> 2) & 3) << 6) | (((lane >> 4) & 1) << 5) | (((lane >> 5) & 1) << 8); }
; template <bool META>
; __device__ __forceinline__ void attn_unit(const bf16_t* Q, bf16_t* Oo, const bf16_t* __restrict__ Kb, const bf16_t* __restrict__ Vb, int b, int kvh, int h, int qb, char* lds, const int tid, const float* qn, const float* RT) {
;   constexpr int NT = 257, LDK = 256;
;   const int wid = tid >> 6, lane = tid & 63, r32 = lane & 31, hi = lane >> 5;
;   bf16_t* V_lds = (bf16_t*)lds; bf16_t* K_lds = (bf16_t*)(lds + 3 * SHM_V);
;   float* ws = (float*)(lds + 3 * SHM_V + 3 * SHM_K) + wid * 64; float* li_l = ws; float* al_l = ws + 32;
;   float m_reg = -1e30f, l_reg = 0; f32x16 o[4] = {}; bf16x8 qr[8];
;   const bf16_t* Kh = Kb + kvh * 128; const bf16_t* Vh = Vb + kvh * 128;
;   const long kv0 = (long)b * SEQ, mrow = NREAL + NMETA * b;
;   { const int sq = qb * 256 + wid * 32 + r32;
;     load_q_roped(Q + (size_t)(b * SEQ + sq) * 1024 + h * 128 + hi * 8, qn + hi * 8, RT, sq >> 6, sq & 63, hi, lane, qr); }
;   const int sr = tid >> 4, sc = (tid & 15) * 8, vst0 = v_st(sr, sc), vst1 = v_st(32 + sr, sc);
;   const int vb0 = (int)(uintptr_t)V_lds + v_rd_base(lane);
;   const unsigned lo0 = (unsigned)(sr * LDK + sc) * 2u;
;   struct { bf16x8 vs0, vs1, ks0, ks1; } sr_[1];
.LBB0_255:
	s_and_b64 vcc, exec, s[0:1]
	s_cbranch_vccz .LBB0_348
	s_cmpk_gt_i32 s50, 0x3ff
	s_cbranch_scc1 .LBB0_274
	v_readlane_b32 s0, v255, 13
	s_lshl_b32 s0, s0, 7
	s_ashr_i32 s1, s0, 31
	s_lshl_b64 s[0:1], s[0:1], 2
	s_add_u32 s0, s68, s0
	s_addc_u32 s1, s69, s1
	v_readlane_b32 s2, v255, 24
	v_readlane_b32 s3, v255, 25
	s_add_u32 s48, s2, 0x3d7f5100
	s_addc_u32 s49, s3, 0
	v_and_b32_e32 v0, 0x3fffffc0, v208
	s_add_i32 s2, 0, 0x18000
	v_lshl_add_u32 v173, v0, 2, s2
	v_ashrrev_i32_e32 v0, 1, v208
	v_and_b32_e32 v2, 63, v208
	v_and_b32_e32 v172, 0xffffffe0, v0
	v_and_b32_e32 v0, 32, v208
	v_lshl_add_u64 v[164:165], s[0:1], 0, v[0:1]
	v_lshlrev_b32_e32 v0, 2, v2
	v_xor_b32_e32 v252, 0x80, v0
	v_ashrrev_i32_e32 v0, 4, v208
	v_and_b32_e32 v5, 0xfffff0, v0
	s_waitcnt vmcnt(0)
	v_lshlrev_b32_e32 v6, 1, v0
	s_waitcnt lgkmcnt(0)
	v_lshlrev_b32_e32 v3, 3, v208
	v_and_or_b32 v5, v6, 8, v5
	v_and_b32_e32 v4, 0x78, v3
	v_lshrrev_b32_e32 v6, 1, v0
	v_lshrrev_b32_e32 v5, 1, v5
	v_bfe_u32 v3, v3, 5, 2
	v_and_b32_e32 v7, 3, v0
	v_or_b32_e32 v5, v5, v3
	v_and_or_b32 v6, v6, 4, v7
	v_lshlrev_b32_e32 v7, 1, v4
	v_lshlrev_b32_e32 v5, 9, v5
	v_lshlrev_b32_e32 v6, 6, v6
	v_and_b32_e32 v8, 48, v7
	v_or3_b32 v176, v5, v6, v8
	v_add_u32_e32 v5, 32, v0
	v_and_b32_e32 v9, 0xfffff0, v5
	v_lshlrev_b32_e32 v10, 1, v5
	v_and_or_b32 v9, v10, 8, v9
	v_lshrrev_b32_e32 v9, 1, v9
	v_or_b32_e32 v3, v9, v3
	v_lshlrev_b32_e32 v3, 9, v3
	v_or3_b32 v177, v3, v6, v8
	v_lshlrev_b32_e32 v6, 4, v208
	v_lshlrev_b32_e32 v3, 3, v2
	v_and_b32_e32 v8, 0xc0, v6
	v_lshlrev_b32_e32 v9, 1, v208
	v_and_or_b32 v8, v3, 24, v8
	v_and_b32_e32 v9, 32, v9
	v_and_b32_e32 v3, 0x100, v3
	s_cmp_lg_u32 0, -1
	v_or3_b32 v3, v8, v9, v3
	s_cselect_b32 s0, 0, 0
	v_lshlrev_b32_e32 v0, 8, v0
	v_add_u32_e32 v178, s0, v3
	v_or_b32_e32 v3, v0, v4
	v_bfe_u32 v11, v208, 5, 1
	v_lshlrev_b32_e32 v166, 1, v3
	v_and_b32_e32 v3, 0xf0, v208
	v_and_b32_e32 v163, 31, v208
	v_bitop3_b32 v179, v7, v0, v3 bitop3:0xde
	v_lshlrev_b32_e32 v0, 8, v5
	v_lshlrev_b32_e32 v181, 4, v11
	v_bitop3_b32 v180, v7, v0, v3 bitop3:0xde
	v_lshlrev_b32_e32 v0, 8, v163
	v_and_b32_e32 v3, 0xf0, v6
	v_or_b32_e32 v4, 32, v181
	v_bitop3_b32 v183, v4, v0, v3 bitop3:0xde
	v_or_b32_e32 v4, 64, v181
	v_bitop3_b32 v184, v4, v0, v3 bitop3:0xde
	v_or_b32_e32 v4, 0x60, v181
	v_bitop3_b32 v185, v4, v0, v3 bitop3:0xde
	v_or_b32_e32 v4, 0x80, v181
	v_bitop3_b32 v186, v4, v0, v3 bitop3:0xde
	v_or_b32_e32 v4, 0xa0, v181
	v_bitop3_b32 v187, v4, v0, v3 bitop3:0xde
	v_or_b32_e32 v4, 0xc0, v181
	v_bitop3_b32 v188, v4, v0, v3 bitop3:0xde
	v_or_b32_e32 v4, 0xe0, v181
	v_lshlrev_b32_e32 v162, 3, v11
	v_mov_b32_e32 v167, v1
	v_bitop3_b32 v182, v181, v0, v3 bitop3:0xde
	v_bitop3_b32 v189, v4, v0, v3 bitop3:0xde
	v_cmp_gt_u32_e64 s[38:39], 32, v2
	v_lshl_add_u32 v190, v163, 2, v173
	v_and_b32_e32 v230, 63, v208
	v_lshrrev_b32_e32 v231, 6, v208
	v_lshlrev_b32_e32 v231, 2, v231
	v_lshrrev_b32_e32 v232, 5, v230
	v_bfe_u32 v233, v230, 2, 1
	v_lshl_add_u32 v234, v232, 1, v231
	v_add_u32_e32 v234, v234, v233
	v_bfe_u32 v235, v230, 3, 2
	v_and_b32_e32 v236, 3, v230
	v_lshl_add_u32 v235, v235, 2, v236
	v_lshlrev_b32_e32 v166, 9, v234
	v_lshl_add_u32 v166, v235, 4, v166
	v_and_b32_e32 v232, 0x13, v234
	v_and_b32_e32 v233, 4, v234
	v_lshlrev_b32_e32 v233, 1, v233
	v_and_b32_e32 v236, 8, v234
	v_lshrrev_b32_e32 v236, 1, v236
	v_or3_b32 v232, v232, v233, v236
	v_lshrrev_b32_e32 v233, 3, v232
	v_lshrrev_b32_e32 v236, 2, v235
	v_lshl_add_u32 v233, v233, 2, v236
	v_lshlrev_b32_e32 v233, 9, v233
	v_and_b32_e32 v236, 7, v232
	v_lshl_add_u32 v233, v236, 6, v233
	v_and_b32_e32 v236, 3, v235
	v_lshl_add_u32 v176, v236, 4, v233
	v_add_u32_e32 v177, 0x2000, v176
	v_bfe_u32 v232, v230, 1, 2
	v_add_u32_e32 v232, v232, v231
	v_lshrrev_b32_e32 v233, 3, v230
	v_and_b32_e32 v236, 1, v230
	v_lshl_add_u32 v233, v233, 1, v236
	v_lshlrev_b32_e32 v184, 9, v232
	v_lshl_add_u32 v184, v233, 4, v184
	v_mov_b32_e32 v185, v1
	v_add_u32_e32 v186, 0x4000, v184
	v_lshrrev_b32_e32 v234, 1, v233
	v_lshlrev_b32_e32 v234, 11, v234
	v_lshl_add_u32 v234, v232, 5, v234
	v_bfe_u32 v235, v232, 3, 1
	v_xor_b32_e32 v235, v235, v236
	v_lshl_or_b32 v179, v235, 4, v234
	v_add_u32_e32 v180, 0x400, v179
	v_and_b32_e32 v232, 31, v208
	v_lshlrev_b32_e32 v233, 5, v232
	v_bfe_u32 v234, v208, 5, 1
	v_bfe_u32 v235, v208, 3, 1
	v_xor_b32_e32 v234, v234, v235
	v_lshl_or_b32 v182, v234, 4, v233
	v_and_b32_e32 v230, 63, v208
	v_lshrrev_b32_e32 v231, 6, v208
	v_and_b32_e32 v232, 31, v230
	v_lshrrev_b32_e32 v232, 2, v232
	v_lshl_add_u32 v232, v231, 3, v232
	v_and_b32_e32 v233, 0x33, v232
	v_and_b32_e32 v234, 4, v232
	v_lshlrev_b32_e32 v234, 1, v234
	v_and_b32_e32 v235, 8, v232
	v_lshrrev_b32_e32 v235, 1, v235
	v_or3_b32 v233, v233, v234, v235
	v_lshrrev_b32_e32 v234, 5, v230
	v_and_b32_e32 v235, 3, v230
	v_lshl_add_u32 v234, v234, 2, v235
	v_lshlrev_b32_e32 v187, 9, v233
	v_lshl_add_u32 v187, v234, 4, v187
	v_lshrrev_b32_e32 v232, 1, v230
	v_lshrrev_b32_e32 v233, 4, v230
	v_xor_b32_e32 v233, v233, v230
	v_and_b32_e32 v233, 1, v233
	v_lshl_add_u32 v233, v231, 1, v233
	v_lshlrev_b32_e32 v188, 9, v232
	v_lshl_add_u32 v188, v233, 4, v188
	s_mov_b32 s2, s50
	s_branch .LBB0_259

; __device__ __forceinline__ float bflo(unsigned w) { return __uint_as_float(w << 16); }
; __device__ __forceinline__ float bfhi(unsigned w) { return __uint_as_float(w & 0xffff0000u); }
; __device__ __forceinline__ float lane_read(float v, int src) { return __int_as_float(__builtin_amdgcn_ds_bpermute(src << 2, __float_as_int(v))); }
; __device__ __forceinline__ void load_q_roped(const bf16_t* Qw, const float* __restrict__ wq, const float* __restrict__ RT, int pr, int pc, int hi, int lane, bf16x8 (&qr)[8]) {
;   float y[8][8]; float ss = 0.f;
; #pragma unroll
;   for (int d0 = 0; d0 < 8; ++d0) { const u32x4 w = *(const u32x4*)(Qw + d0 * 16);
; #pragma unroll
;     for (int q = 0; q < 4; ++q) { y[d0][2 * q] = bflo(w[q]); y[d0][2 * q + 1] = bfhi(w[q]); } }
; #pragma unroll
;   for (int d0 = 0; d0 < 8; ++d0)
; #pragma unroll
;     for (int e = 0; e < 8; ++e) ss += y[d0][e] * y[d0][e];
;   ss += lane_read(ss, lane ^ 32);
;   const float rstd = __builtin_amdgcn_rsqf(ss * (1.f / 128.f) + 1e-6f);
; #pragma unroll
;   for (int d0 = 0; d0 < 8; ++d0) { const f32x4 w0 = *(const f32x4*)(wq + d0 * 16), w1 = *(const f32x4*)(wq + d0 * 16 + 4);
; #pragma unroll
;     for (int e = 0; e < 8; ++e) y[d0][e] *= rstd * (e < 4 ? w0[e & 3] : w1[e & 3]); }
.LBB0_259:
	s_bfe_u32 s1, s2, 0x10008
	s_ashr_i32 s0, s2, 9
	s_lshl_b32 s3, s1, 8
	v_readlane_b32 s6, v255, 9
	v_readlane_b32 s7, v255, 10
	s_add_u32 s40, s6, s3
	s_addc_u32 s41, s7, 0
	v_readlane_b32 s6, v255, 5
	v_readlane_b32 s7, v255, 6
	s_add_u32 s42, s6, s3
	s_addc_u32 s43, s7, 0
	s_lshl_b32 s3, s2, 6
	s_and_b32 s3, s3, 0x3f00
	v_add_u32_e32 v191, s3, v172
	v_or_b32_e32 v21, v191, v163
	s_lshl_b32 s3, s0, 14
	v_add_u32_e32 v2, s3, v21
	s_lshl_b32 s4, s2, 7
	v_ashrrev_i32_e32 v3, 31, v2
	s_lshl_b32 s1, s1, 9
	s_and_b32 s4, s4, 0x180
	v_lshlrev_b64 v[2:3], 11, v[2:3]
	s_or_b32 s30, s1, s4
	v_lshl_add_u64 v[2:3], s[20:21], 0, v[2:3]
	s_lshl_b32 s4, s30, 1
	v_lshl_add_u64 v[2:3], v[2:3], 0, s[4:5]
	v_lshlrev_b32_e32 v0, 1, v162
	v_lshl_add_u64 v[18:19], v[2:3], 0, v[0:1]
	global_load_dwordx4 v[58:61], v[18:19], off offset:160
	global_load_dwordx4 v[62:65], v[18:19], off offset:224
	global_load_dwordx4 v[66:69], v[18:19], off offset:128
	global_load_dwordx4 v[70:73], v[18:19], off offset:192
	global_load_dwordx4 v[2:5], v[164:165], off
	global_load_dwordx4 v[6:9], v[164:165], off offset:16
	global_load_dwordx4 v[10:13], v[164:165], off offset:64
	global_load_dwordx4 v[82:85], v[164:165], off offset:80
	global_load_dwordx4 v[86:89], v[164:165], off offset:128
	global_load_dwordx4 v[90:93], v[164:165], off offset:144
	global_load_dwordx4 v[94:97], v[164:165], off offset:192
	global_load_dwordx4 v[98:101], v[164:165], off offset:208
	global_load_dwordx4 v[102:105], v[164:165], off offset:256
	global_load_dwordx4 v[106:109], v[164:165], off offset:272
	global_load_dwordx4 v[50:53], v[18:19], off offset:32
	global_load_dwordx4 v[110:113], v[164:165], off offset:320
	global_load_dwordx4 v[114:117], v[164:165], off offset:336
	global_load_dwordx4 v[54:57], v[18:19], off offset:96
	global_load_dwordx4 v[118:121], v[164:165], off offset:384
	global_load_dwordx4 v[122:125], v[164:165], off offset:400
	global_load_dwordx4 v[126:129], v[164:165], off offset:448
	global_load_dwordx4 v[14:17], v[164:165], off offset:464
	global_load_dwordx4 v[74:77], v[18:19], off
	s_lshl_b32 s4, s0, 4
	s_add_i32 s31, s4, 0x8000
	v_ashrrev_i32_e32 v0, 1, v191
	s_movk_i32 s4, 0xffe0
	v_and_or_b32 v20, v0, s4, v162
	v_lshlrev_b32_e32 v0, 5, v21
	v_ashrrev_i32_e32 v21, 31, v20
	v_or_b32_e32 v22, 16, v20
	v_lshl_add_u64 v[20:21], v[20:21], 3, s[48:49]
	global_load_dwordx4 v[78:81], v[18:19], off offset:64
	global_load_dwordx4 v[30:33], v[20:21], off offset:48
	global_load_dwordx4 v[38:41], v[20:21], off offset:32
	global_load_dwordx4 v[42:45], v[20:21], off offset:16
	global_load_dwordx4 v[46:49], v[20:21], off
	s_movk_i32 s4, 0x7e0
	v_and_or_b32 v0, v0, s4, v162
	v_lshlrev_b32_e32 v195, 3, v0
	v_mov_b32_e32 v196, v245
	v_mov_b64_e32 v[244:245], v[242:243]
	v_mov_b64_e32 v[174:175], v[248:249]
	v_ashrrev_i32_e32 v23, 31, v22
	v_lshl_add_u64 v[34:35], v[22:23], 3, s[48:49]
	global_load_dwordx4 v[18:21], v[34:35], off offset:48
	global_load_dwordx4 v[22:25], v[34:35], off offset:32
	global_load_dwordx4 v[26:29], v[34:35], off offset:16
	s_nop 0
	global_load_dwordx4 v[34:37], v[34:35], off
	s_ashr_i32 s1, s0, 31
	s_lshl_b64 s[90:91], s[0:1], 14
	s_ashr_i32 s44, s31, 31
	s_lshl_b64 s[0:1], s[0:1], 23
	s_add_u32 s6, s42, s0
	s_addc_u32 s7, s43, s1
	s_add_u32 s8, s40, s0
	s_addc_u32 s9, s41, s1
	s_mov_b32 s4, s5
	s_mov_b32 s10, s5
	s_mov_b32 s11, s5
	s_mov_b32 s12, s5
	s_mov_b32 s13, s5
	s_mov_b32 s14, s5
	s_mov_b32 s15, s5
	s_mov_b32 s16, s5
	s_mov_b32 s17, s5
	s_mov_b32 s18, s5
	s_mov_b32 s19, s5
	s_mov_b32 s28, 1
	s_waitcnt vmcnt(0)
	v_lshlrev_b32_e32 v142, 16, v58
	v_and_b32_e32 v143, 0xffff0000, v58
	v_lshlrev_b32_e32 v226, 16, v66
	v_and_b32_e32 v227, 0xffff0000, v66
	v_lshlrev_b32_e32 v218, 16, v67
	v_and_b32_e32 v219, 0xffff0000, v67
	v_pk_mul_f32 v[66:67], v[226:227], v[226:227]
	v_pk_mul_f32 v[222:223], v[218:219], v[218:219]
	v_lshlrev_b32_e32 v214, 16, v68
	v_and_b32_e32 v215, 0xffff0000, v68
	v_lshlrev_b32_e32 v144, 16, v69
	v_and_b32_e32 v145, 0xffff0000, v69
	v_pk_mul_f32 v[68:69], v[214:215], v[214:215]
	v_pk_mul_f32 v[210:211], v[144:145], v[144:145]
	v_lshlrev_b32_e32 v202, 16, v51
	v_and_b32_e32 v203, 0xffff0000, v51
	v_lshlrev_b32_e32 v150, 16, v50
	v_and_b32_e32 v151, 0xffff0000, v50
	v_lshlrev_b32_e32 v238, 16, v52
	v_and_b32_e32 v239, 0xffff0000, v52
	v_lshlrev_b32_e32 v230, 16, v53
	v_and_b32_e32 v231, 0xffff0000, v53
	v_lshlrev_b32_e32 v158, 16, v74
	v_and_b32_e32 v159, 0xffff0000, v74
	v_lshlrev_b32_e32 v156, 16, v75
	v_and_b32_e32 v157, 0xffff0000, v75
	v_pk_mul_f32 v[50:51], v[158:159], v[158:159]
	v_lshlrev_b32_e32 v154, 16, v76
	v_add_f32_e32 v0, v50, v51
	v_pk_mul_f32 v[50:51], v[156:157], v[156:157]
	v_and_b32_e32 v155, 0xffff0000, v76
	v_add_f32_e32 v0, v50, v0
	v_add_f32_e32 v0, v51, v0
	v_pk_mul_f32 v[50:51], v[154:155], v[154:155]
	v_lshlrev_b32_e32 v152, 16, v77
	v_and_b32_e32 v153, 0xffff0000, v77
	v_add_f32_e32 v0, v50, v0
	v_add_f32_e32 v0, v51, v0
	v_pk_mul_f32 v[50:51], v[152:153], v[152:153]
	v_pk_mul_f32 v[52:53], v[238:239], v[238:239]
	v_add_f32_e32 v0, v50, v0
	v_add_f32_e32 v0, v51, v0
	v_pk_mul_f32 v[50:51], v[150:151], v[150:151]
	v_pk_mul_f32 v[234:235], v[230:231], v[230:231]
	v_add_f32_e32 v0, v50, v0
	v_add_f32_e32 v0, v51, v0
	v_pk_mul_f32 v[50:51], v[202:203], v[202:203]
	v_lshlrev_b32_e32 v242, 16, v78
	v_add_f32_e32 v0, v50, v0
	v_add_f32_e32 v0, v51, v0
	v_add_f32_e32 v0, v52, v0
	v_add_f32_e32 v0, v53, v0
	v_and_b32_e32 v243, 0xffff0000, v78
	v_add_f32_e32 v0, v234, v0
	v_lshlrev_b32_e32 v198, 16, v55
	v_and_b32_e32 v199, 0xffff0000, v55
	v_lshlrev_b32_e32 v200, 16, v54
	v_and_b32_e32 v201, 0xffff0000, v54
; __device__ __forceinline__ float lane_read(float v, int src) { return __int_as_float(__builtin_amdgcn_ds_bpermute(src << 2, __float_as_int(v))); }
; __device__ __forceinline__ void load_q_roped(const bf16_t* Qw, const float* __restrict__ wq, const float* __restrict__ RT, int pr, int pc, int hi, int lane, bf16x8 (&qr)[8]) {
;     ...
;     for (int e = 0; e < 8; ++e) ss += y[d0][e] * y[d0][e];
;   ss += lane_read(ss, lane ^ 32);
;   const float rstd = __builtin_amdgcn_rsqf(ss * (1.f / 128.f) + 1e-6f);
; #pragma unroll
;   for (int d0 = 0; d0 < 8; ++d0) { const f32x4 w0 = *(const f32x4*)(wq + d0 * 16), w1 = *(const f32x4*)(wq + d0 * 16 + 4);
; #pragma unroll
;     for (int e = 0; e < 8; ++e) y[d0][e] *= rstd * (e < 4 ? w0[e & 3] : w1[e & 3]); }
; #pragma unroll
;   for (int hf = 0; hf < 2; ++hf)
; #pragma unroll
;     for (int lo = 0; lo < 2; ++lo) { const int d0 = hf * 4 + lo;
;       const float* tp = RT + (size_t)((hf ? pc : pr) * 32 + lo * 16 + hi * 8) * 2;
;       f32x4 t[4];
; #pragma unroll
;       for (int q = 0; q < 4; ++q) t[q] = *(const f32x4*)(tp + 4 * q);
; #pragma unroll
;       for (int e = 0; e < 8; ++e) { const float cs = t[e >> 1][(e & 1) * 2], sn = t[e >> 1][(e & 1) * 2 + 1];
;         const float x1 = y[d0][e], x2 = y[d0 + 2][e]; y[d0][e] = x1 * cs - x2 * sn; y[d0 + 2][e] = x1 * sn + x2 * cs; } }
	v_add_f32_e32 v0, v235, v0
	v_pk_mul_f32 v[54:55], v[242:243], v[242:243]
	v_lshlrev_b32_e32 v248, 16, v79
	v_and_b32_e32 v249, 0xffff0000, v79
	v_add_f32_e32 v0, v54, v0
	v_add_f32_e32 v0, v55, v0
	v_pk_mul_f32 v[54:55], v[248:249], v[248:249]
	v_lshlrev_b32_e32 v206, 16, v80
	v_and_b32_e32 v207, 0xffff0000, v80
	v_add_f32_e32 v0, v54, v0
	v_add_f32_e32 v0, v55, v0
	v_pk_mul_f32 v[54:55], v[206:207], v[206:207]
	v_lshlrev_b32_e32 v204, 16, v81
	v_and_b32_e32 v205, 0xffff0000, v81
	v_add_f32_e32 v0, v54, v0
	v_add_f32_e32 v0, v55, v0
	v_pk_mul_f32 v[54:55], v[204:205], v[204:205]
	v_pk_mul_f32 v[52:53], v[200:201], v[200:201]
	v_add_f32_e32 v0, v54, v0
	v_add_f32_e32 v0, v55, v0
	v_add_f32_e32 v0, v52, v0
	v_pk_mul_f32 v[50:51], v[198:199], v[198:199]
	v_add_f32_e32 v0, v53, v0
	v_lshlrev_b32_e32 v240, 16, v56
	v_and_b32_e32 v241, 0xffff0000, v56
	v_add_f32_e32 v0, v50, v0
	v_lshlrev_b32_e32 v232, 16, v57
	v_and_b32_e32 v233, 0xffff0000, v57
	v_pk_mul_f32 v[56:57], v[240:241], v[240:241]
	v_add_f32_e32 v0, v51, v0
	v_add_f32_e32 v0, v56, v0
	v_pk_mul_f32 v[236:237], v[232:233], v[232:233]
	v_add_f32_e32 v0, v57, v0
	v_add_f32_e32 v0, v236, v0
	v_add_f32_e32 v0, v237, v0
	v_add_f32_e32 v0, v66, v0
	v_add_f32_e32 v0, v67, v0
	v_add_f32_e32 v0, v222, v0
	v_add_f32_e32 v0, v223, v0
	v_add_f32_e32 v0, v68, v0
	v_add_f32_e32 v0, v69, v0
	v_add_f32_e32 v0, v210, v0
	v_pk_mul_f32 v[168:169], v[142:143], v[142:143]
	v_add_f32_e32 v0, v211, v0
	v_lshlrev_b32_e32 v138, 16, v59
	v_and_b32_e32 v139, 0xffff0000, v59
	v_add_f32_e32 v0, v168, v0
	v_pk_mul_f32 v[148:149], v[138:139], v[138:139]
	v_add_f32_e32 v0, v169, v0
	v_lshlrev_b32_e32 v136, 16, v60
	v_and_b32_e32 v137, 0xffff0000, v60
	v_add_f32_e32 v0, v148, v0
	v_lshlrev_b32_e32 v140, 16, v63
	v_and_b32_e32 v141, 0xffff0000, v63
	v_lshlrev_b32_e32 v146, 16, v62
	v_and_b32_e32 v147, 0xffff0000, v62
	v_pk_mul_f32 v[62:63], v[136:137], v[136:137]
	v_add_f32_e32 v0, v149, v0
	v_lshlrev_b32_e32 v134, 16, v61
	v_and_b32_e32 v135, 0xffff0000, v61
	v_add_f32_e32 v0, v62, v0
	v_pk_mul_f32 v[58:59], v[134:135], v[134:135]
	v_add_f32_e32 v0, v63, v0
	v_lshlrev_b32_e32 v228, 16, v70
	v_and_b32_e32 v229, 0xffff0000, v70
	v_add_f32_e32 v0, v58, v0
	v_lshlrev_b32_e32 v220, 16, v71
	v_and_b32_e32 v221, 0xffff0000, v71
	v_pk_mul_f32 v[70:71], v[228:229], v[228:229]
	v_add_f32_e32 v0, v59, v0
	v_add_f32_e32 v0, v70, v0
	v_pk_mul_f32 v[224:225], v[220:221], v[220:221]
	v_add_f32_e32 v0, v71, v0
	v_lshlrev_b32_e32 v216, 16, v72
	v_and_b32_e32 v217, 0xffff0000, v72
	v_add_f32_e32 v0, v224, v0
	v_lshlrev_b32_e32 v192, 16, v73
	v_and_b32_e32 v193, 0xffff0000, v73
	v_pk_mul_f32 v[72:73], v[216:217], v[216:217]
	v_add_f32_e32 v0, v225, v0
	v_add_f32_e32 v0, v72, v0
	v_pk_mul_f32 v[212:213], v[192:193], v[192:193]
	v_add_f32_e32 v0, v73, v0
	v_add_f32_e32 v0, v212, v0
	v_pk_mul_f32 v[170:171], v[146:147], v[146:147]
	v_add_f32_e32 v0, v213, v0
	v_add_f32_e32 v0, v170, v0
	v_pk_mul_f32 v[160:161], v[140:141], v[140:141]
	v_add_f32_e32 v0, v171, v0
	v_lshlrev_b32_e32 v132, 16, v64
	v_and_b32_e32 v133, 0xffff0000, v64
	v_add_f32_e32 v0, v160, v0
	v_lshlrev_b32_e32 v130, 16, v65
	v_and_b32_e32 v131, 0xffff0000, v65
	v_pk_mul_f32 v[64:65], v[132:133], v[132:133]
	v_add_f32_e32 v0, v161, v0
	v_add_f32_e32 v0, v64, v0
	v_pk_mul_f32 v[60:61], v[130:131], v[130:131]
	v_add_f32_e32 v0, v65, v0
	v_add_f32_e32 v0, v60, v0
	v_add_f32_e32 v0, v61, v0
	ds_bpermute_b32 v50, v252, v0
	global_load_dwordx4 v[66:69], v195, s[48:49] offset:48
	global_load_dwordx4 v[70:73], v195, s[48:49] offset:32
	global_load_dwordx4 v[74:77], v195, s[48:49] offset:16
	global_load_dwordx4 v[78:81], v195, s[48:49]
	v_add_u32_e32 v168, 0, v176
	v_add_u32_e32 v169, 0, v177
	v_lshl_add_u64 v[170:171], s[40:41], 0, v[166:167]
	s_waitcnt lgkmcnt(0)
	v_add_f32_e32 v0, v0, v50
	v_mov_b32_e32 v50, 0x358637bd
	v_fmamk_f32 v0, v0, 0x3c000000, v50
	v_rsq_f32_e32 v0, v0
	global_load_dwordx4 v[50:53], v195, s[48:49] offset:176
	global_load_dwordx4 v[54:57], v195, s[48:49] offset:160
	global_load_dwordx4 v[58:61], v195, s[48:49] offset:144
	global_load_dwordx4 v[62:65], v195, s[48:49] offset:128
	v_pk_mul_f32 v[14:15], v[14:15], v[0:1] op_sel_hi:[1,0]
	v_pk_mul_f32 v[126:127], v[126:127], v[0:1] op_sel_hi:[1,0]
	v_pk_mul_f32 v[116:117], v[116:117], v[0:1] op_sel_hi:[1,0]
	v_pk_mul_f32 v[86:87], v[86:87], v[0:1] op_sel_hi:[1,0]
	v_pk_mul_f32 v[14:15], v[14:15], v[132:133]
	v_pk_mul_f32 v[132:133], v[126:127], v[146:147]
	v_pk_mul_f32 v[126:127], v[116:117], v[134:135]
	v_pk_mul_f32 v[114:115], v[114:115], v[0:1] op_sel_hi:[1,0]
	v_pk_mul_f32 v[112:113], v[112:113], v[0:1] op_sel_hi:[1,0]
	v_pk_mul_f32 v[90:91], v[90:91], v[0:1] op_sel_hi:[1,0]
	v_pk_mul_f32 v[116:117], v[86:87], v[242:243]
	v_lshl_add_u64 v[86:87], s[6:7], 0, v[166:167]
	v_pk_mul_f32 v[134:135], v[114:115], v[136:137]
	v_pk_mul_f32 v[136:137], v[112:113], v[138:139]
	v_pk_mul_f32 v[110:111], v[110:111], v[0:1] op_sel_hi:[1,0]
	v_pk_mul_f32 v[108:109], v[108:109], v[0:1] op_sel_hi:[1,0]
	v_pk_mul_f32 v[106:107], v[106:107], v[0:1] op_sel_hi:[1,0]
	v_pk_mul_f32 v[112:113], v[90:91], v[206:207]
	v_add_co_u32_e32 v90, vcc, s37, v86
	v_pk_mul_f32 v[138:139], v[110:111], v[142:143]
	v_pk_mul_f32 v[142:143], v[108:109], v[144:145]
	v_pk_mul_f32 v[144:145], v[106:107], v[214:215]
	v_pk_mul_f32 v[104:105], v[104:105], v[0:1] op_sel_hi:[1,0]
	v_pk_mul_f32 v[102:103], v[102:103], v[0:1] op_sel_hi:[1,0]
	v_pk_mul_f32 v[92:93], v[92:93], v[0:1] op_sel_hi:[1,0]
	v_pk_mul_f32 v[88:89], v[88:89], v[0:1] op_sel_hi:[1,0]
	v_addc_co_u32_e32 v91, vcc, 0, v87, vcc
	v_lshl_add_u64 v[106:107], s[8:9], 0, v[184:185]
; __device__ __forceinline__ unsigned cvtpk(float lo, float hi) { const f32x2c v = {lo, hi}; const bf16x2c r = __builtin_convertvector(v, bf16x2c); return __builtin_bit_cast(unsigned, r); }
; __device__ __forceinline__ void load_q_roped(const bf16_t* Qw, const float* __restrict__ wq, const float* __restrict__ RT, int pr, int pc, int hi, int lane, bf16x8 (&qr)[8]) {
;     ...
; #pragma unroll
;   for (int hf = 0; hf < 2; ++hf)
; #pragma unroll
;     for (int lo = 0; lo < 2; ++lo) { const int d0 = hf * 4 + lo;
;       const float* tp = RT + (size_t)((hf ? pc : pr) * 32 + lo * 16 + hi * 8) * 2;
;       f32x4 t[4];
; #pragma unroll
;       for (int q = 0; q < 4; ++q) t[q] = *(const f32x4*)(tp + 4 * q);
; #pragma unroll
;       for (int e = 0; e < 8; ++e) { const float cs = t[e >> 1][(e & 1) * 2], sn = t[e >> 1][(e & 1) * 2 + 1];
;         const float x1 = y[d0][e], x2 = y[d0 + 2][e]; y[d0][e] = x1 * cs - x2 * sn; y[d0 + 2][e] = x1 * sn + x2 * cs; } }
; #pragma unroll
;   for (int d0 = 0; d0 < 8; ++d0) { u32x4 w; w.x = cvtpk(y[d0][0], y[d0][1]); w.y = cvtpk(y[d0][2], y[d0][3]); w.z = cvtpk(y[d0][4], y[d0][5]); w.w = cvtpk(y[d0][6], y[d0][7]);
;     qr[d0] = *reinterpret_cast<bf16x8*>(&w); }
	v_pk_mul_f32 v[146:147], v[104:105], v[218:219]
	v_pk_mul_f32 v[148:149], v[102:103], v[226:227]
	v_pk_mul_f32 v[110:111], v[92:93], v[204:205]
	v_pk_mul_f32 v[114:115], v[88:89], v[248:249]
	global_load_dwordx4 v[86:89], v[86:87], off
	s_nop 0
	global_load_dwordx4 v[90:93], v[90:91], off
	v_pk_mul_f32 v[128:129], v[128:129], v[0:1] op_sel_hi:[1,0]
	global_load_dwordx4 v[102:105], v[106:107], off
	v_add_co_u32_e32 v106, vcc, s37, v106
	v_pk_mul_f32 v[120:121], v[120:121], v[0:1] op_sel_hi:[1,0]
	s_nop 0
	v_addc_co_u32_e32 v107, vcc, 0, v107, vcc
	global_load_dwordx4 v[106:109], v[106:107], off
	v_pk_mul_f32 v[2:3], v[2:3], v[0:1] op_sel_hi:[1,0]
	v_pk_mul_f32 v[128:129], v[128:129], v[140:141]
	v_pk_mul_f32 v[140:141], v[120:121], v[220:221]
	v_pk_mul_f32 v[120:121], v[2:3], v[158:159]
	v_pk_mul_f32 v[2:3], v[16:17], v[0:1] op_sel_hi:[1,0]
	v_mov_b32_e32 v17, v48
	v_mov_b32_e32 v48, v47
	v_mov_b32_e32 v16, v46
	v_pk_mul_f32 v[46:47], v[48:49], v[116:117]
	v_pk_mul_f32 v[4:5], v[4:5], v[0:1] op_sel_hi:[1,0]
	v_pk_fma_f32 v[46:47], v[16:17], v[120:121], v[46:47] neg_lo:[0,0,1] neg_hi:[0,0,1]
	v_pk_mul_f32 v[16:17], v[16:17], v[116:117]
	v_pk_mul_f32 v[4:5], v[4:5], v[156:157]
	v_pk_fma_f32 v[16:17], v[48:49], v[120:121], v[16:17]
	v_mov_b32_e32 v49, v44
	v_mov_b32_e32 v44, v43
	v_mov_b32_e32 v48, v42
	v_pk_mul_f32 v[42:43], v[44:45], v[114:115]
	v_pk_mul_f32 v[6:7], v[6:7], v[0:1] op_sel_hi:[1,0]
	v_pk_fma_f32 v[42:43], v[48:49], v[4:5], v[42:43] neg_lo:[0,0,1] neg_hi:[0,0,1]
	v_pk_mul_f32 v[48:49], v[48:49], v[114:115]
	v_pk_mul_f32 v[6:7], v[6:7], v[154:155]
	v_pk_fma_f32 v[114:115], v[44:45], v[4:5], v[48:49]
	v_mov_b32_e32 v5, v40
	v_mov_b32_e32 v40, v39
	v_mov_b32_e32 v4, v38
	v_pk_mul_f32 v[38:39], v[40:41], v[112:113]
	v_pk_mul_f32 v[8:9], v[8:9], v[0:1] op_sel_hi:[1,0]
	v_pk_fma_f32 v[38:39], v[4:5], v[6:7], v[38:39] neg_lo:[0,0,1] neg_hi:[0,0,1]
	v_pk_mul_f32 v[4:5], v[4:5], v[112:113]
	v_pk_mul_f32 v[8:9], v[8:9], v[152:153]
	v_pk_fma_f32 v[112:113], v[40:41], v[6:7], v[4:5]
	v_mov_b32_e32 v5, v32
	v_mov_b32_e32 v32, v31
	v_mov_b32_e32 v4, v30
	v_pk_mul_f32 v[6:7], v[32:33], v[110:111]
	v_pk_mul_f32 v[94:95], v[94:95], v[0:1] op_sel_hi:[1,0]
	v_pk_fma_f32 v[30:31], v[4:5], v[8:9], v[6:7] neg_lo:[0,0,1] neg_hi:[0,0,1]
	v_pk_mul_f32 v[4:5], v[4:5], v[110:111]
	v_pk_mul_f32 v[94:95], v[94:95], v[200:201]
	v_pk_mul_f32 v[10:11], v[10:11], v[0:1] op_sel_hi:[1,0]
	v_pk_fma_f32 v[110:111], v[32:33], v[8:9], v[4:5]
	v_mov_b32_e32 v5, v36
	v_mov_b32_e32 v36, v35
	v_pk_mul_f32 v[10:11], v[10:11], v[150:151]
	v_mov_b32_e32 v4, v34
	v_pk_mul_f32 v[6:7], v[36:37], v[94:95]
	v_pk_mul_f32 v[96:97], v[96:97], v[0:1] op_sel_hi:[1,0]
	v_pk_fma_f32 v[116:117], v[4:5], v[10:11], v[6:7] neg_lo:[0,0,1] neg_hi:[0,0,1]
	v_pk_mul_f32 v[4:5], v[4:5], v[94:95]
	v_pk_mul_f32 v[96:97], v[96:97], v[198:199]
	v_pk_mul_f32 v[12:13], v[12:13], v[0:1] op_sel_hi:[1,0]
	v_pk_fma_f32 v[94:95], v[36:37], v[10:11], v[4:5]
	v_mov_b32_e32 v5, v28
	v_mov_b32_e32 v28, v27
	v_pk_mul_f32 v[12:13], v[12:13], v[202:203]
	v_mov_b32_e32 v4, v26
	v_pk_mul_f32 v[6:7], v[28:29], v[96:97]
	v_pk_mul_f32 v[98:99], v[98:99], v[0:1] op_sel_hi:[1,0]
	v_pk_fma_f32 v[120:121], v[4:5], v[12:13], v[6:7] neg_lo:[0,0,1] neg_hi:[0,0,1]
	v_pk_mul_f32 v[4:5], v[4:5], v[96:97]
	v_pk_mul_f32 v[98:99], v[98:99], v[240:241]
	v_pk_mul_f32 v[82:83], v[82:83], v[0:1] op_sel_hi:[1,0]
	v_pk_fma_f32 v[12:13], v[28:29], v[12:13], v[4:5]
	v_mov_b32_e32 v5, v24
	v_mov_b32_e32 v24, v23
	v_pk_mul_f32 v[82:83], v[82:83], v[238:239]
	v_mov_b32_e32 v4, v22
	v_pk_mul_f32 v[6:7], v[24:25], v[98:99]
	v_pk_mul_f32 v[100:101], v[100:101], v[0:1] op_sel_hi:[1,0]
	v_pk_fma_f32 v[96:97], v[4:5], v[82:83], v[6:7] neg_lo:[0,0,1] neg_hi:[0,0,1]
	v_pk_mul_f32 v[4:5], v[4:5], v[98:99]
	v_pk_mul_f32 v[124:125], v[124:125], v[0:1] op_sel_hi:[1,0]
	v_pk_mul_f32 v[122:123], v[122:123], v[0:1] op_sel_hi:[1,0]
	v_pk_mul_f32 v[118:119], v[118:119], v[0:1] op_sel_hi:[1,0]
	v_pk_mul_f32 v[100:101], v[100:101], v[232:233]
	v_pk_mul_f32 v[84:85], v[84:85], v[0:1] op_sel_hi:[1,0]
	v_pk_fma_f32 v[82:83], v[24:25], v[82:83], v[4:5]
	v_mov_b32_e32 v5, v20
	v_mov_b32_e32 v20, v19
	v_add_u32_e32 v0, 0, v179
	v_pk_mul_f32 v[84:85], v[84:85], v[230:231]
	v_mov_b32_e32 v4, v18
	v_pk_mul_f32 v[6:7], v[20:21], v[100:101]
	s_waitcnt vmcnt(0)
	s_waitcnt vmcnt(3)
	ds_write_b128 v168, v[86:89]
	s_waitcnt vmcnt(2)
	ds_write_b128 v169, v[90:93]
	s_waitcnt vmcnt(1)
	ds_write_b128 v0, v[102:105] offset:49152
	v_add_u32_e32 v0, 0, v180
	v_pk_mul_f32 v[2:3], v[2:3], v[130:131]
	v_pk_fma_f32 v[130:131], v[4:5], v[84:85], v[6:7] neg_lo:[0,0,1] neg_hi:[0,0,1]
	v_pk_mul_f32 v[4:5], v[4:5], v[100:101]
	s_waitcnt vmcnt(0)
	ds_write_b128 v0, v[106:109] offset:49152
	v_add_u32_e32 v0, 0, v182
	v_pk_fma_f32 v[84:85], v[20:21], v[84:85], v[4:5]
	s_waitcnt lgkmcnt(0)
	s_barrier
; __device__ __forceinline__ unsigned cvtpk(float lo, float hi) { const f32x2c v = {lo, hi}; const bf16x2c r = __builtin_convertvector(v, bf16x2c); return __builtin_bit_cast(unsigned, r); }
; __device__ __forceinline__ void qkt(f32x16& p0, f32x16& p1, const bf16_t* Ks, const bf16x8* qr, int r32, int hi) {
;   p0 = f32x16{}; p1 = f32x16{};
; #pragma unroll
;   for (int d0 = 0; d0 < 8; ++d0) { int cb = (d0 * 16 + hi * 8) * 2;
;     bf16x8 b0 = *reinterpret_cast<const bf16x8*>((const char*)Ks + KSWZ(r32, cb));
;     bf16x8 b1 = *reinterpret_cast<const bf16x8*>((const char*)Ks + KSWZ(32 + r32, cb));
;     p0 = __builtin_amdgcn_mfma_f32_32x32x16_bf16(b0, qr[d0], p0, 0, 0, 0);
;     p1 = __builtin_amdgcn_mfma_f32_32x32x16_bf16(b1, qr[d0], p1, 0, 0, 0); }
; }
; __device__ __forceinline__ void load_q_roped(const bf16_t* Qw, const float* __restrict__ wq, const float* __restrict__ RT, int pr, int pc, int hi, int lane, bf16x8 (&qr)[8]) {
;     ...
; #pragma unroll
;   for (int d0 = 0; d0 < 8; ++d0) { u32x4 w; w.x = cvtpk(y[d0][0], y[d0][1]); w.y = cvtpk(y[d0][2], y[d0][3]); w.z = cvtpk(y[d0][4], y[d0][5]); w.w = cvtpk(y[d0][6], y[d0][7]);
;     qr[d0] = *reinterpret_cast<bf16x8*>(&w); }
	ds_read_b128 v[4:7], v0 offset:49152
	v_pk_mul_f32 v[118:119], v[118:119], v[228:229]
	v_mov_b32_e32 v9, v80
	v_mov_b32_e32 v80, v79
	v_mov_b32_e32 v8, v78
	v_pk_mul_f32 v[10:11], v[80:81], v[118:119]
	v_cvt_pk_bf16_f32 v98, v46, v47
	v_cvt_pk_bf16_f32 v99, v42, v43
	v_cvt_pk_bf16_f32 v100, v38, v39
	v_cvt_pk_bf16_f32 v101, v30, v31
	v_mov_b32_e32 v89, v76
	v_mov_b32_e32 v76, v75
	v_pk_fma_f32 v[78:79], v[8:9], v[148:149], v[10:11] neg_lo:[0,0,1] neg_hi:[0,0,1]
	v_pk_mul_f32 v[86:87], v[8:9], v[118:119]
	ds_read_b128 v[8:11], v0 offset:50176
	s_waitcnt lgkmcnt(1)
	v_mfma_f32_32x32x16_bf16 v[18:33], v[4:7], v[98:101], 0
	v_mov_b32_e32 v88, v74
	v_mul_f32_e64 v4, v76, v140
	v_mul_f32_e64 v5, v77, v141
	v_add_u32_e32 v0, 0, v182
	v_fma_f32 v74, v88, v146, -v4
	v_fma_f32 v75, v89, v147, -v5
	ds_read_b128 v[4:7], v0 offset:51200
	v_pk_mul_f32 v[122:123], v[122:123], v[216:217]
	v_mov_b32_e32 v91, v72
	v_cvt_pk_bf16_f32 v102, v116, v117
	v_cvt_pk_bf16_f32 v103, v120, v121
	v_cvt_pk_bf16_f32 v104, v96, v97
	v_cvt_pk_bf16_f32 v105, v130, v131
	v_mov_b32_e32 v72, v71
	s_waitcnt lgkmcnt(1)
	v_mfma_f32_32x32x16_bf16 v[34:49], v[8:11], v[98:101], 0
	v_mov_b32_e32 v90, v70
	ds_read_b128 v[8:11], v0 offset:52224
	v_add_u32_e32 v0, 0, v182
	v_cvt_pk_bf16_f32 v106, v16, v17
	v_cvt_pk_bf16_f32 v107, v114, v115
	v_cvt_pk_bf16_f32 v108, v112, v113
	v_cvt_pk_bf16_f32 v109, v110, v111
	s_waitcnt lgkmcnt(1)
	v_mfma_f32_32x32x16_bf16 v[18:33], v[4:7], v[102:105], v[18:33]
	v_mul_f32_e64 v4, v72, v122
	v_mul_f32_e64 v5, v73, v123
	v_cvt_pk_bf16_f32 v110, v94, v95
	v_fma_f32 v70, v90, v144, -v4
	v_fma_f32 v71, v91, v145, -v5
	ds_read_b128 v[4:7], v0 offset:53248
	v_cvt_pk_bf16_f32 v111, v12, v13
	v_cvt_pk_bf16_f32 v112, v82, v83
	v_cvt_pk_bf16_f32 v113, v84, v85
	s_waitcnt lgkmcnt(1)
	v_mfma_f32_32x32x16_bf16 v[34:49], v[8:11], v[102:105], v[34:49]
	ds_read_b128 v[8:11], v0 offset:54272
	v_add_u32_e32 v0, 0, v182
	v_mov_b32_e32 v97, v60
	v_mov_b32_e32 v60, v59
	v_mov_b32_e32 v96, v58
	v_pk_mul_f32 v[124:125], v[124:125], v[192:193]
	v_mov_b32_e32 v93, v68
	s_waitcnt lgkmcnt(1)
	v_mfma_f32_32x32x16_bf16 v[18:33], v[4:7], v[106:109], v[18:33]
	ds_read_b128 v[4:7], v0 offset:55296
	v_mov_b32_e32 v68, v67
	v_mov_b32_e32 v92, v66
	v_mul_f32_e64 v66, v68, v124
	v_mul_f32_e64 v67, v69, v125
	v_mov_b32_e32 v59, v56
	v_pk_fma_f32 v[16:17], v[92:93], v[142:143], v[66:67] neg_lo:[0,0,1] neg_hi:[0,0,1]
	v_mov_b32_e32 v56, v55
	s_waitcnt lgkmcnt(1)
	v_mfma_f32_32x32x16_bf16 v[34:49], v[8:11], v[106:109], v[34:49]
	ds_read_b128 v[8:11], v0 offset:56320
	v_add_u32_e32 v0, 0, v182
	v_cvt_pk_bf16_f32 v114, v78, v79
	v_cvt_pk_bf16_f32 v115, v74, v75
	v_cvt_pk_bf16_f32 v116, v70, v71
	v_cvt_pk_bf16_f32 v117, v16, v17
	v_mov_b32_e32 v58, v54
	s_waitcnt lgkmcnt(1)
	v_mfma_f32_32x32x16_bf16 v[18:33], v[4:7], v[110:113], v[18:33]
	v_mul_f32_e64 v4, v60, v128
	v_mul_f32_e64 v5, v61, v129
	v_mov_b32_e32 v67, v64
	v_fma_f32 v12, v96, v136, -v4
	v_fma_f32 v13, v97, v137, -v5
	ds_read_b128 v[4:7], v0 offset:57344
	v_mov_b32_e32 v64, v63
	v_mov_b32_e32 v55, v52
	v_mov_b32_e32 v52, v51
	s_waitcnt lgkmcnt(1)
	v_mfma_f32_32x32x16_bf16 v[34:49], v[8:11], v[110:113], v[34:49]
	ds_read_b128 v[8:11], v0 offset:58368
	v_add_u32_e32 v0, 0, v182
	v_mov_b32_e32 v66, v62
	v_mul_f32_e64 v62, v64, v132
	v_mul_f32_e64 v63, v65, v133
	v_mov_b32_e32 v54, v50
	v_pk_fma_f32 v[62:63], v[66:67], v[138:139], v[62:63] neg_lo:[0,0,1] neg_hi:[0,0,1]
	v_cvt_pk_bf16_f32 v119, v12, v13
	s_waitcnt lgkmcnt(1)
	v_mfma_f32_32x32x16_bf16 v[18:33], v[4:7], v[114:117], v[18:33]
	v_mul_f32_e64 v4, v56, v14
	v_mul_f32_e64 v5, v57, v15
	v_cvt_pk_bf16_f32 v118, v62, v63
	v_fma_f32 v16, v58, v134, -v4
	v_fma_f32 v17, v59, v135, -v5
	ds_read_b128 v[4:7], v0 offset:59392
	v_cvt_pk_bf16_f32 v120, v16, v17
	v_pk_fma_f32 v[12:13], v[80:81], v[148:149], v[86:87]
	v_pk_mul_f32 v[14:15], v[58:59], v[14:15]
	s_waitcnt lgkmcnt(1)
	v_mfma_f32_32x32x16_bf16 v[34:49], v[8:11], v[114:117], v[34:49]
	v_mul_f32_e64 v8, v52, v2
	v_mul_f32_e64 v9, v53, v3
	v_mul_f32_e64 v2, v54, v2
	v_mul_f32_e64 v3, v55, v3
	v_fma_f32 v8, v54, v126, -v8
	v_fma_f32 v9, v55, v127, -v9
	v_pk_fma_f32 v[2:3], v[52:53], v[126:127], v[2:3]
	v_cvt_pk_bf16_f32 v121, v8, v9
	ds_read_b128 v[8:11], v0 offset:60416
	v_add_u32_e32 v0, 0, v182
	s_waitcnt lgkmcnt(1)
	v_mfma_f32_32x32x16_bf16 v[18:33], v[4:7], v[118:121], v[18:33]
	v_mul_f32_e64 v4, v88, v140
	v_mul_f32_e64 v5, v89, v141
	v_mov_b64_e32 v[248:249], v[174:175]
	v_fma_f32 v16, v76, v146, v4
	v_fma_f32 v17, v77, v147, v5
	v_pk_mul_f32 v[4:5], v[90:91], v[122:123]
	v_cvt_pk_bf16_f32 v122, v12, v13
	v_pk_fma_f32 v[50:51], v[72:73], v[144:145], v[4:5]
	ds_read_b128 v[4:7], v0 offset:61440
	s_waitcnt lgkmcnt(1)
	v_mfma_f32_32x32x16_bf16 v[34:49], v[8:11], v[118:121], v[34:49]
	v_mul_f32_e64 v8, v92, v124
	v_mul_f32_e64 v9, v93, v125
	v_cvt_pk_bf16_f32 v123, v16, v17
	v_fma_f32 v8, v68, v142, v8
	v_fma_f32 v9, v69, v143, v9
	v_cvt_pk_bf16_f32 v124, v50, v51
	v_cvt_pk_bf16_f32 v125, v8, v9
	ds_read_b128 v[8:11], v0 offset:62464
	v_add_u32_e32 v0, 0, v182
	s_waitcnt lgkmcnt(1)
	v_mfma_f32_32x32x16_bf16 v[18:33], v[4:7], v[122:125], v[18:33]
	v_mul_f32_e64 v4, v66, v132
	v_mul_f32_e64 v5, v67, v133
	v_mov_b64_e32 v[242:243], v[244:245]
	v_fma_f32 v12, v64, v138, v4
	v_fma_f32 v13, v65, v139, v5
	v_pk_mul_f32 v[4:5], v[96:97], v[128:129]
	v_cvt_pk_bf16_f32 v126, v12, v13
	v_pk_fma_f32 v[16:17], v[60:61], v[136:137], v[4:5]
	ds_read_b128 v[4:7], v0 offset:63488
	s_waitcnt lgkmcnt(1)
; #define SLOAD(i, t) do { const long rb_ = TROW(t); const char* vt_ = (const char*)Vh + rb_ * (LDK * 2); const char* kt_ = (const char*)Kh + rb_ * (LDK * 2); \
;     sr_[i].vs0 = *(const bf16x8*)(vt_ + lo0); sr_[i].vs1 = *(const bf16x8*)(vt_ + lo0 + 32 * LDK * 2); \
;     sr_[i].ks0 = *(const bf16x8*)(kt_ + lo0); sr_[i].ks1 = *(const bf16x8*)(kt_ + lo0 + 32 * LDK * 2); } while (0)
; #define SWRITE(bb, i) do { *(bf16x8*)((char*)V_lds + (bb) * SHM_V + vst0) = sr_[i].vs0;          \
;     *(bf16x8*)((char*)V_lds + (bb) * SHM_V + vst1) = sr_[i].vs1; int kc = sc * 2;               \
;     *(bf16x8*)((char*)K_lds + (bb) * SHM_K + KSWZ(sr, kc)) = sr_[i].ks0;                       \
;     *(bf16x8*)((char*)K_lds + (bb) * SHM_K + KSWZ(32 + sr, kc)) = sr_[i].ks1; } while (0)
; __device__ __forceinline__ void partialSM(f32x16& p0, f32x16& p1, float& m_reg, float& mn, float& alpha) {
;   constexpr float C = ASCALE * 1.4426950408889634f;
;   float pmax = p0[0];
; #pragma unroll
;   for (int r = 1; r < 16; ++r) pmax = fmaxf(pmax, p0[r]);
; #pragma unroll
;   for (int r = 0; r < 16; ++r) pmax = fmaxf(pmax, p1[r]);
;   { auto rr = __builtin_amdgcn_permlane32_swap(__float_as_uint(pmax), __float_as_uint(pmax), false, false);
;     pmax = fmaxf(__uint_as_float(rr[0]), __uint_as_float(rr[1])); }
;   if (__builtin_expect(__all(pmax - m_reg <= ATHR / ASCALE), 1)) { mn = m_reg; alpha = 1.f; }
;   else { mn = fmaxf(m_reg, pmax); alpha = __builtin_amdgcn_exp2f((m_reg - mn) * C); m_reg = mn; }
;   float mnC = -mn * C;
; #pragma unroll
;   for (int r = 0; r < 16; ++r) p0[r] = fmaf(p0[r], C, mnC);
; #pragma unroll
;   for (int r = 0; r < 16; ++r) p1[r] = fmaf(p1[r], C, mnC);
; #pragma unroll
;   for (int r = 0; r < 16; ++r) p0[r] = __builtin_amdgcn_exp2f(p0[r]);
; }
; template <bool META>
; __device__ __forceinline__ void attn_unit(const bf16_t* Q, bf16_t* Oo, const bf16_t* __restrict__ Kb, const bf16_t* __restrict__ Vb, int b, int kvh, int h, int qb, char* lds, const int tid, const float* qn, const float* RT) {
;     ...
;   f32x16 pA0, pA1, pB0, pB1; float mnA, mnB, alA, alB; bf16x8 pa0, pa1, pa2, pa3;
;   constexpr int SE = 0, SO = 0;
;   SLOAD(SE, 0); asm volatile("s_waitcnt vmcnt(0)" ::: "memory"); SWRITE(0, SE); __syncthreads();
;   qkt(pA0, pA1, K_lds, qr, r32, hi); partialSM(pA0, pA1, m_reg, mnA, alA);
;   SLOAD(SO, 1);
;   SWAIT(); SWRITE(1, SO); __syncthreads();
;   int bc = 1;
	v_mfma_f32_32x32x16_bf16 v[34:49], v[8:11], v[122:125], v[34:49]
	v_fma_f32 v8, v56, v134, v14
	v_fma_f32 v9, v57, v135, v15
	v_cvt_pk_bf16_f32 v127, v16, v17
	v_cvt_pk_bf16_f32 v128, v8, v9
	v_cvt_pk_bf16_f32 v129, v2, v3
	ds_read_b128 v[8:11], v0 offset:64512
	v_mov_b32_e32 v245, v196
	s_waitcnt lgkmcnt(1)
	v_mfma_f32_32x32x16_bf16 v[18:33], v[4:7], v[126:129], v[18:33]
	s_waitcnt lgkmcnt(0)
	v_mfma_f32_32x32x16_bf16 v[34:49], v[8:11], v[126:129], v[34:49]
	s_nop 9
	v_max_f32_e32 v0, v19, v19
	v_max_f32_e32 v2, v18, v18
	v_max_f32_e32 v0, v2, v0
	v_max3_f32 v0, v0, v20, v21
	v_max3_f32 v0, v0, v22, v23
	v_max3_f32 v0, v0, v24, v25
	v_max3_f32 v0, v0, v26, v27
	v_max3_f32 v0, v0, v28, v29
	v_max3_f32 v0, v0, v30, v31
	v_max3_f32 v0, v0, v32, v33
	v_max3_f32 v0, v0, v34, v35
	v_max3_f32 v0, v0, v36, v37
	v_max3_f32 v0, v0, v38, v39
	v_max3_f32 v0, v0, v40, v41
	v_max3_f32 v0, v0, v42, v43
	v_max3_f32 v0, v0, v44, v45
	v_max3_f32 v0, v0, v46, v47
	v_max3_f32 v0, v0, v48, v49
	v_mov_b32_e32 v2, v0
	s_nop 1
	v_permlane32_swap_b32_e32 v0, v2
	v_max_f32_e32 v2, v2, v2
	v_max_f32_e32 v0, v0, v0
	v_max_f32_e32 v0, v0, v2
	v_add_f32_e32 v2, 0x7149f2ca, v0
	v_cmp_ge_f32_e32 vcc, s25, v2
	s_cmp_eq_u64 vcc, exec
	s_cselect_b64 vcc, -1, 0
	s_bitset1_b32 s0, 15
	s_add_u32 s6, s42, s0
	s_addc_u32 s7, s43, s1
	s_add_u32 s8, s40, s0
	v_lshl_add_u64 v[2:3], s[6:7], 0, v[166:167]
	s_addc_u32 s9, s41, s1
	v_add_co_u32_e64 v4, s[0:1], s37, v2
	v_max_f32_e32 v0, 0xf149f2ca, v0
	s_nop 0
	v_addc_co_u32_e64 v5, s[0:1], 0, v3, s[0:1]
	global_load_dwordx4 v[50:53], v[2:3], off
	global_load_dwordx4 v[54:57], v[4:5], off
	v_lshl_add_u64 v[2:3], s[8:9], 0, v[184:185]
	global_load_dwordx4 v[58:61], v[2:3], off
	v_add_co_u32_e64 v2, s[0:1], s37, v2
	v_cndmask_b32_e32 v150, v0, v246, vcc
	s_nop 0
	v_addc_co_u32_e64 v3, s[0:1], 0, v3, s[0:1]
	global_load_dwordx4 v[62:65], v[2:3], off
	v_sub_f32_e32 v2, 0xf149f2ca, v0
	v_mul_f32_e32 v2, 0x3e0293ee, v2
	v_exp_f32_e32 v66, v2
	v_mul_f32_e32 v0, 0xbe0293ee, v150
	v_fmamk_f32 v18, v18, 0x3e0293ee, v0
	v_fmamk_f32 v19, v19, 0x3e0293ee, v0
	v_cndmask_b32_e64 v192, v66, 1.0, vcc
	v_mov_b32_e32 v66, v0
	v_fmamk_f32 v20, v20, 0x3e0293ee, v0
	v_fmamk_f32 v21, v21, 0x3e0293ee, v0
	v_fmamk_f32 v22, v22, 0x3e0293ee, v0
	v_fmamk_f32 v23, v23, 0x3e0293ee, v0
	v_fmamk_f32 v24, v24, 0x3e0293ee, v0
	v_fmamk_f32 v25, v25, 0x3e0293ee, v0
	v_fmamk_f32 v26, v26, 0x3e0293ee, v0
	v_fmamk_f32 v27, v27, 0x3e0293ee, v0
	v_fmamk_f32 v28, v28, 0x3e0293ee, v0
	v_fmamk_f32 v29, v29, 0x3e0293ee, v0
	v_fmamk_f32 v30, v30, 0x3e0293ee, v0
	v_fmamk_f32 v31, v31, 0x3e0293ee, v0
	v_fmamk_f32 v32, v32, 0x3e0293ee, v0
	v_fmac_f32_e32 v66, 0x3e0293ee, v33
	s_add_i32 s0, 0, 0x10000
	s_mov_b32 s6, s5
	s_mov_b32 s7, s5
	s_mov_b32 s8, s5
	s_mov_b32 s9, s5
	v_mov_b64_e32 v[2:3], s[4:5]
	v_pk_fma_f32 v[130:131], v[48:49], s[36:37], v[0:1] op_sel_hi:[1,0,0]
	v_pk_fma_f32 v[132:133], v[46:47], s[36:37], v[0:1] op_sel_hi:[1,0,0]
	v_pk_fma_f32 v[134:135], v[44:45], s[36:37], v[0:1] op_sel_hi:[1,0,0]
	v_pk_fma_f32 v[136:137], v[42:43], s[36:37], v[0:1] op_sel_hi:[1,0,0]
	v_pk_fma_f32 v[138:139], v[40:41], s[36:37], v[0:1] op_sel_hi:[1,0,0]
	v_pk_fma_f32 v[140:141], v[38:39], s[36:37], v[0:1] op_sel_hi:[1,0,0]
	v_pk_fma_f32 v[142:143], v[36:37], s[36:37], v[0:1] op_sel_hi:[1,0,0]
	v_pk_fma_f32 v[144:145], v[34:35], s[36:37], v[0:1] op_sel_hi:[1,0,0]
	v_exp_f32_e32 v146, v18
	v_exp_f32_e32 v147, v19
	v_exp_f32_e32 v148, v20
	v_exp_f32_e32 v159, v21
	v_exp_f32_e32 v160, v22
	v_exp_f32_e32 v209, v23
	v_exp_f32_e32 v149, v24
	v_exp_f32_e32 v161, v25
	v_exp_f32_e32 v151, v26
	v_exp_f32_e32 v153, v27
	v_exp_f32_e32 v154, v28
	v_exp_f32_e32 v157, v29
	v_exp_f32_e32 v152, v30
	v_exp_f32_e32 v155, v31
	v_exp_f32_e32 v156, v32
	v_exp_f32_e32 v158, v66
	v_add_u32_e32 v0, s0, v179
	v_mov_b64_e32 v[16:17], s[18:19]
	s_waitcnt vmcnt(0)
	s_waitcnt vmcnt(3)
	ds_write_b128 v168, v[50:53] offset:16384
	s_waitcnt vmcnt(2)
	ds_write_b128 v169, v[54:57] offset:16384
	v_mov_b64_e32 v[4:5], s[6:7]
	s_waitcnt vmcnt(1)
	ds_write_b128 v0, v[58:61]
	v_add_u32_e32 v0, s0, v180
	v_mov_b64_e32 v[6:7], s[8:9]
	v_mov_b64_e32 v[8:9], s[10:11]
	v_mov_b64_e32 v[10:11], s[12:13]
	v_mov_b64_e32 v[12:13], s[14:15]
	v_mov_b64_e32 v[14:15], s[16:17]
	s_waitcnt vmcnt(0)
	ds_write_b128 v0, v[62:65]
	v_mov_b64_e32 v[64:65], v[16:17]
	v_mov_b64_e32 v[48:49], v[16:17]
	v_mov_b64_e32 v[32:33], v[16:17]
	v_lshl_add_u64 v[168:169], s[42:43], 0, v[166:167]
	s_mov_b64 s[12:13], s[42:43]
	s_mov_b64 s[14:15], s[40:41]
	v_lshrrev_b32_e32 v239, 6, v208
	s_nop 0
	v_readfirstlane_b32 s18, v239
	s_lshl_b32 s18, s18, 11
	v_add_u32_e32 v238, 0x4000, v166
	s_bitset1_b32 s90, 7
	v_mov_b32_e32 v0, 0
	s_mov_b32 s4, -1
	v_mov_b64_e32 v[62:63], v[14:15]
	v_mov_b64_e32 v[60:61], v[12:13]
	v_mov_b64_e32 v[58:59], v[10:11]
	v_mov_b64_e32 v[56:57], v[8:9]
	v_mov_b64_e32 v[54:55], v[6:7]
	v_mov_b64_e32 v[52:53], v[4:5]
	v_mov_b64_e32 v[50:51], v[2:3]
	v_mov_b64_e32 v[46:47], v[14:15]
	v_mov_b64_e32 v[44:45], v[12:13]
	v_mov_b64_e32 v[42:43], v[10:11]
	v_mov_b64_e32 v[40:41], v[8:9]
	v_mov_b64_e32 v[38:39], v[6:7]
	v_mov_b64_e32 v[36:37], v[4:5]
	v_mov_b64_e32 v[34:35], v[2:3]
	v_mov_b64_e32 v[30:31], v[14:15]
	v_mov_b64_e32 v[28:29], v[12:13]
	v_mov_b64_e32 v[26:27], v[10:11]
	v_mov_b64_e32 v[24:25], v[8:9]
	v_mov_b64_e32 v[22:23], v[6:7]
	v_mov_b64_e32 v[20:21], v[4:5]
	v_mov_b64_e32 v[18:19], v[2:3]
	s_waitcnt lgkmcnt(0)
	s_barrier
; #define SBAR() __builtin_amdgcn_sched_barrier(0)
; #define SLOAD(i, t) do { const long rb_ = TROW(t); const char* vt_ = (const char*)Vh + rb_ * (LDK * 2); const char* kt_ = (const char*)Kh + rb_ * (LDK * 2); \
;     sr_[i].vs0 = *(const bf16x8*)(vt_ + lo0); sr_[i].vs1 = *(const bf16x8*)(vt_ + lo0 + 32 * LDK * 2); \
;     sr_[i].ks0 = *(const bf16x8*)(kt_ + lo0); sr_[i].ks1 = *(const bf16x8*)(kt_ + lo0 + 32 * LDK * 2); } while (0)
; __device__ __forceinline__ void finishSM(f32x16& p0, f32x16& p1, float alpha, float& l_reg, bf16x8& pa0, bf16x8& pa1, bf16x8& pa2, bf16x8& pa3) {
; #pragma unroll
;   for (int r = 0; r < 16; ++r) p1[r] = __builtin_amdgcn_exp2f(p1[r]);
;   float ps = 0;
; #pragma unroll
;   for (int r = 0; r < 16; ++r) ps += p0[r];
; #pragma unroll
;   for (int r = 0; r < 16; ++r) ps += p1[r];
;   { auto rr = __builtin_amdgcn_permlane32_swap(__float_as_uint(ps), __float_as_uint(ps), false, false);
;     ps = __uint_as_float(rr[0]) + __uint_as_float(rr[1]); }
;   l_reg = l_reg * alpha + ps;
;     ...
;   PK4(p0, 0, pa0); PK4(p0, 8, pa1); PK4(p1, 0, pa2); PK4(p1, 8, pa3);
;     ...
; }
; __device__ __forceinline__ void qkt(f32x16& p0, f32x16& p1, const bf16_t* Ks, const bf16x8* qr, int r32, int hi) {
;   p0 = f32x16{}; p1 = f32x16{};
; #pragma unroll
;   for (int d0 = 0; d0 < 8; ++d0) { int cb = (d0 * 16 + hi * 8) * 2;
;     bf16x8 b0 = *reinterpret_cast<const bf16x8*>((const char*)Ks + KSWZ(r32, cb));
;     bf16x8 b1 = *reinterpret_cast<const bf16x8*>((const char*)Ks + KSWZ(32 + r32, cb));
;     p0 = __builtin_amdgcn_mfma_f32_32x32x16_bf16(b0, qr[d0], p0, 0, 0, 0);
;     p1 = __builtin_amdgcn_mfma_f32_32x32x16_bf16(b1, qr[d0], p1, 0, 0, 0); }
; }
; template <bool META>
; __device__ __forceinline__ void attn_unit(const bf16_t* Q, bf16_t* Oo, const bf16_t* __restrict__ Kb, const bf16_t* __restrict__ Vb, int b, int kvh, int h, int qb, char* lds, const int tid, const float* qn, const float* RT) {
;     ...
;   for (int j = 1; j + 1 < NT; j += 2) {
;     const int bn = bc == 2 ? 0 : bc + 1, bp = bc == 0 ? 2 : bc - 1;
;     SBAR(); qkt(pB0, pB1, (bf16_t*)((char*)K_lds + bc * SHM_K), qr, r32, hi);
;     finishSM(pA0, pA1, alA, l_reg, pa0, pa1, pa2, pa3); SBAR();
;     SLOAD(SO, j + 1);
;     SBAR();
;     pv_d0(o, vb0 + bp * (int)SHM_V, pa0, pa1, pa2, pa3); partialSM(pB0, pB1, m_reg, mnB, alB);
.LBB0_260:
	s_mov_b32 s6, s28
	v_sub_co_u32_e64 v66, s[0:1], s6, 1
	s_and_b64 s[0:1], s[0:1], exec
	v_readfirstlane_b32 s0, v66
	s_cselect_b32 s28, 2, s0
	s_lshl_b32 s9, s6, 14
	s_add_i32 s0, s9, 0
	v_add_u32_e32 v195, s0, v182
	ds_read_b128 v[66:69], v195 offset:49152
	ds_read_b128 v[70:73], v195 offset:50176
	ds_read_b128 v[210:213], v195 offset:51200
	ds_read_b128 v[214:217], v195 offset:52224
	s_waitcnt lgkmcnt(3)
	v_mfma_f32_32x32x16_bf16 v[82:97], v[66:69], v[98:101], 0
	v_exp_f32_e32 v144, v144
	v_exp_f32_e32 v145, v145
	v_exp_f32_e32 v142, v142
	v_exp_f32_e32 v143, v143
	v_exp_f32_e32 v140, v140
	v_exp_f32_e32 v141, v141
	v_exp_f32_e32 v138, v138
	s_waitcnt lgkmcnt(2)
	v_mfma_f32_32x32x16_bf16 v[66:81], v[70:73], v[98:101], 0
	v_exp_f32_e32 v139, v139
	v_exp_f32_e32 v136, v136
	v_exp_f32_e32 v137, v137
	v_exp_f32_e32 v134, v134
	v_exp_f32_e32 v135, v135
	v_exp_f32_e32 v132, v132
	v_exp_f32_e32 v133, v133
	s_waitcnt lgkmcnt(1)
	v_mfma_f32_32x32x16_bf16 v[82:97], v[210:213], v[102:105], v[82:97]
	v_exp_f32_e32 v130, v130
	v_exp_f32_e32 v131, v131
	s_waitcnt lgkmcnt(0)
	v_mfma_f32_32x32x16_bf16 v[66:81], v[214:217], v[102:105], v[66:81]
	ds_read_b128 v[210:213], v195 offset:53248
	ds_read_b128 v[214:217], v195 offset:54272
	s_waitcnt lgkmcnt(1)
	v_mfma_f32_32x32x16_bf16 v[82:97], v[210:213], v[106:109], v[82:97]
	s_waitcnt lgkmcnt(0)
	v_mfma_f32_32x32x16_bf16 v[66:81], v[214:217], v[106:109], v[66:81]
	ds_read_b128 v[210:213], v195 offset:55296
	ds_read_b128 v[214:217], v195 offset:56320
	s_waitcnt lgkmcnt(1)
	v_mfma_f32_32x32x16_bf16 v[82:97], v[210:213], v[110:113], v[82:97]
	s_waitcnt lgkmcnt(0)
	v_mfma_f32_32x32x16_bf16 v[66:81], v[214:217], v[110:113], v[66:81]
	ds_read_b128 v[210:213], v195 offset:57344
	ds_read_b128 v[214:217], v195 offset:58368
	s_waitcnt lgkmcnt(1)
	v_mfma_f32_32x32x16_bf16 v[82:97], v[210:213], v[114:117], v[82:97]
	s_waitcnt lgkmcnt(0)
	v_mfma_f32_32x32x16_bf16 v[66:81], v[214:217], v[114:117], v[66:81]
	ds_read_b128 v[210:213], v195 offset:59392
	ds_read_b128 v[214:217], v195 offset:60416
	s_waitcnt lgkmcnt(1)
	v_mfma_f32_32x32x16_bf16 v[82:97], v[210:213], v[118:121], v[82:97]
	s_waitcnt lgkmcnt(0)
	v_mfma_f32_32x32x16_bf16 v[66:81], v[214:217], v[118:121], v[66:81]
	ds_read_b128 v[210:213], v195 offset:61440
	ds_read_b128 v[214:217], v195 offset:62464
	s_waitcnt lgkmcnt(1)
	v_mfma_f32_32x32x16_bf16 v[82:97], v[210:213], v[122:125], v[82:97]
	s_waitcnt lgkmcnt(0)
	v_mfma_f32_32x32x16_bf16 v[66:81], v[214:217], v[122:125], v[66:81]
	ds_read_b128 v[210:213], v195 offset:63488
	ds_read_b128 v[214:217], v195 offset:64512
	v_add_f32_e32 v193, v147, v146
	v_add_f32_e32 v193, v148, v193
	v_add_f32_e32 v193, v159, v193
	v_add_f32_e32 v193, v160, v193
	v_add_f32_e32 v193, v209, v193
	v_add_f32_e32 v193, v149, v193
	v_add_f32_e32 v193, v161, v193
	v_add_f32_e32 v193, v151, v193
	v_add_f32_e32 v193, v153, v193
	v_add_f32_e32 v193, v154, v193
	v_add_f32_e32 v193, v157, v193
	v_add_f32_e32 v193, v152, v193
	v_add_f32_e32 v193, v155, v193
	v_add_f32_e32 v193, v156, v193
	v_add_f32_e32 v193, v158, v193
	v_add_f32_e32 v193, v144, v193
	v_add_f32_e32 v193, v145, v193
	v_add_f32_e32 v193, v142, v193
	v_add_f32_e32 v193, v143, v193
	v_add_f32_e32 v193, v140, v193
	v_add_f32_e32 v193, v141, v193
	v_add_f32_e32 v193, v138, v193
	v_add_f32_e32 v193, v139, v193
	v_add_f32_e32 v193, v136, v193
	v_add_f32_e32 v193, v137, v193
	s_waitcnt lgkmcnt(1)
	v_mfma_f32_32x32x16_bf16 v[82:97], v[210:213], v[126:129], v[82:97]
	v_add_f32_e32 v193, v134, v193
	v_add_f32_e32 v193, v135, v193
	v_add_f32_e32 v193, v132, v193
	v_add_f32_e32 v193, v133, v193
	v_add_f32_e32 v193, v130, v193
	v_add_f32_e32 v193, v131, v193
	v_mov_b32_e32 v195, v193
	s_waitcnt lgkmcnt(0)
	v_mfma_f32_32x32x16_bf16 v[66:81], v[214:217], v[126:129], v[66:81]
	v_cvt_pk_bf16_f32 v146, v146, v147
	v_cvt_pk_bf16_f32 v147, v148, v159
	v_cvt_pk_bf16_f32 v148, v160, v209
	v_permlane32_swap_b32_e32 v193, v195
	v_cvt_pk_bf16_f32 v149, v149, v161
	v_permlane32_swap_b32_e32 v146, v148
	v_cvt_pk_bf16_f32 v210, v151, v153
	v_cvt_pk_bf16_f32 v211, v154, v157
	v_cvt_pk_bf16_f32 v212, v152, v155
	v_cvt_pk_bf16_f32 v213, v156, v158
	v_cvt_pk_bf16_f32 v152, v144, v145
	v_cvt_pk_bf16_f32 v153, v142, v143
	v_cvt_pk_bf16_f32 v154, v140, v141
	v_cvt_pk_bf16_f32 v155, v138, v139
	v_cvt_pk_bf16_f32 v156, v136, v137
	v_cvt_pk_bf16_f32 v157, v134, v135
	v_cvt_pk_bf16_f32 v158, v132, v133
	v_cvt_pk_bf16_f32 v159, v130, v131
	v_permlane32_swap_b32_e32 v147, v149
	v_permlane32_swap_b32_e32 v210, v212
	v_permlane32_swap_b32_e32 v211, v213
	v_permlane32_swap_b32_e32 v152, v154
	v_permlane32_swap_b32_e32 v153, v155
	v_permlane32_swap_b32_e32 v156, v158
	v_permlane32_swap_b32_e32 v157, v159
	s_cmpk_lg_i32 s4, 0xfd
	s_cselect_b64 s[0:1], -1, 0
	s_cmpk_eq_i32 s4, 0xfd
	s_cselect_b64 s[40:41], -1, 0
	s_and_b64 s[10:11], s[40:41], exec
	s_cselect_b32 s11, s44, s91
	s_cselect_b32 s10, s31, s90
	s_lshl_b64 s[10:11], s[10:11], 9
	s_add_i32 s19, s9, 0x4000
	s_cmp_lg_u32 s6, 2
	s_cselect_b32 s19, s19, 0
	s_add_i32 s19, s19, s18
	s_add_u32 s16, s12, s10
	s_addc_u32 s17, s13, s11
	s_mov_b32 m0, s19
	s_nop 0
	global_load_lds_dwordx4 v187, s[16:17]
	s_add_i32 m0, s19, 0x380
	s_nop 0
	global_load_lds_dwordx4 v187, s[16:17] offset:128
	s_add_u32 s16, s14, s10
	s_addc_u32 s17, s15, s11
	s_add_i32 m0, s19, 0xc000
	s_nop 0
	global_load_lds_dwordx4 v188, s[16:17]
	s_add_u32 s16, s16, 0x4000
	s_addc_u32 s17, s17, 0
	s_add_i32 m0, s19, 0xc400
	s_nop 0
	global_load_lds_dwordx4 v188, s[16:17]
	s_lshl_b32 s8, s28, 14
	v_add_u32_e32 v151, s8, v178
	ds_read_b64_tr_b16 v[214:215], v151 offset:0
	ds_read_b64_tr_b16 v[216:217], v151 offset:0x800
	ds_read_b64_tr_b16 v[218:219], v151 offset:0x1000
	ds_read_b64_tr_b16 v[220:221], v151 offset:0x1800
	ds_read_b64_tr_b16 v[222:223], v151 offset:0x2000
	ds_read_b64_tr_b16 v[224:225], v151 offset:0x2800
	ds_read_b64_tr_b16 v[226:227], v151 offset:0x3000
	ds_read_b64_tr_b16 v[228:229], v151 offset:0x3800
	s_waitcnt lgkmcnt(6)
; #define SBAR() __builtin_amdgcn_sched_barrier(0)
; __device__ __forceinline__ void partialSM(f32x16& p0, f32x16& p1, float& m_reg, float& mn, float& alpha) {
;   constexpr float C = ASCALE * 1.4426950408889634f;
;   float pmax = p0[0];
; #pragma unroll
;   for (int r = 1; r < 16; ++r) pmax = fmaxf(pmax, p0[r]);
; #pragma unroll
;   for (int r = 0; r < 16; ++r) pmax = fmaxf(pmax, p1[r]);
;   { auto rr = __builtin_amdgcn_permlane32_swap(__float_as_uint(pmax), __float_as_uint(pmax), false, false);
;     pmax = fmaxf(__uint_as_float(rr[0]), __uint_as_float(rr[1])); }
;   if (__builtin_expect(__all(pmax - m_reg <= ATHR / ASCALE), 1)) { mn = m_reg; alpha = 1.f; }
;   else { mn = fmaxf(m_reg, pmax); alpha = __builtin_amdgcn_exp2f((m_reg - mn) * C); m_reg = mn; }
; template <int D0> __device__ __forceinline__ void pv_one(f32x16& od, int vb, bf16x8 pa0, bf16x8 pa1, bf16x8 pa2, bf16x8 pa3) {
;   const s16x4 l0 = tr_read<v_rd_off(D0, 0, 0)>(vb), h0 = tr_read<v_rd_off(D0, 0, 1)>(vb), l1 = tr_read<v_rd_off(D0, 1, 0)>(vb), h1 = tr_read<v_rd_off(D0, 1, 1)>(vb);
;   const s16x4 l2 = tr_read<v_rd_off(D0, 2, 0)>(vb), h2 = tr_read<v_rd_off(D0, 2, 1)>(vb), l3 = tr_read<v_rd_off(D0, 3, 0)>(vb), h3 = tr_read<v_rd_off(D0, 3, 1)>(vb);
;   asm volatile("s_waitcnt lgkmcnt(0)" ::: "memory"); SBAR();
;     ...
;   od = __builtin_amdgcn_mfma_f32_32x32x16_bf16(pa0, PK(l0, h0), od, 0, 0, 0);
;   od = __builtin_amdgcn_mfma_f32_32x32x16_bf16(pa1, PK(l1, h1), od, 0, 0, 0);
;   od = __builtin_amdgcn_mfma_f32_32x32x16_bf16(pa2, PK(l2, h2), od, 0, 0, 0);
;   od = __builtin_amdgcn_mfma_f32_32x32x16_bf16(pa3, PK(l3, h3), od, 0, 0, 0);
;     ...
; }
; __device__ __forceinline__ void pv_d0(f32x16* o, int vb, bf16x8 pa0, bf16x8 pa1, bf16x8 pa2, bf16x8 pa3) {
;   pv_one<0>(o[0], vb, pa0, pa1, pa2, pa3); pv_one<1>(o[1], vb, pa0, pa1, pa2, pa3); pv_one<2>(o[2], vb, pa0, pa1, pa2, pa3); pv_one<3>(o[3], vb, pa0, pa1, pa2, pa3);
	s_nop 0
	v_mfma_f32_32x32x16_bf16 v[2:17], v[146:149], v[214:217], v[2:17]
	ds_read_b64_tr_b16 v[214:215], v151 offset:0x200
	ds_read_b64_tr_b16 v[216:217], v151 offset:0xa00
	s_waitcnt lgkmcnt(6)
	v_mfma_f32_32x32x16_bf16 v[2:17], v[210:213], v[218:221], v[2:17]
	ds_read_b64_tr_b16 v[218:219], v151 offset:0x1200
	ds_read_b64_tr_b16 v[220:221], v151 offset:0x1a00
	s_waitcnt lgkmcnt(6)
	v_mfma_f32_32x32x16_bf16 v[2:17], v[152:155], v[222:225], v[2:17]
	ds_read_b64_tr_b16 v[222:223], v151 offset:0x2200
	ds_read_b64_tr_b16 v[224:225], v151 offset:0x2a00
	s_waitcnt lgkmcnt(6)
	v_mfma_f32_32x32x16_bf16 v[2:17], v[156:159], v[226:229], v[2:17]
	ds_read_b64_tr_b16 v[226:227], v151 offset:0x3200
	ds_read_b64_tr_b16 v[228:229], v151 offset:0x3a00
	s_waitcnt lgkmcnt(6)
	v_mfma_f32_32x32x16_bf16 v[50:65], v[146:149], v[214:217], v[50:65]
	ds_read_b64_tr_b16 v[214:215], v151 offset:0x400
	ds_read_b64_tr_b16 v[216:217], v151 offset:0xc00
	s_waitcnt lgkmcnt(6)
	v_mfma_f32_32x32x16_bf16 v[50:65], v[210:213], v[218:221], v[50:65]
	ds_read_b64_tr_b16 v[218:219], v151 offset:0x1400
	ds_read_b64_tr_b16 v[220:221], v151 offset:0x1c00
	s_waitcnt lgkmcnt(6)
	v_mfma_f32_32x32x16_bf16 v[50:65], v[152:155], v[222:225], v[50:65]
	ds_read_b64_tr_b16 v[222:223], v151 offset:0x2400
	ds_read_b64_tr_b16 v[224:225], v151 offset:0x2c00
	s_waitcnt lgkmcnt(6)
	v_mfma_f32_32x32x16_bf16 v[50:65], v[156:159], v[226:229], v[50:65]
	ds_read_b64_tr_b16 v[226:227], v151 offset:0x3400
	ds_read_b64_tr_b16 v[228:229], v151 offset:0x3c00
	s_waitcnt lgkmcnt(6)
	v_mfma_f32_32x32x16_bf16 v[34:49], v[146:149], v[214:217], v[34:49]
	ds_read_b64_tr_b16 v[214:215], v151 offset:0x600
	ds_read_b64_tr_b16 v[216:217], v151 offset:0xe00
	s_waitcnt lgkmcnt(6)
	v_mfma_f32_32x32x16_bf16 v[34:49], v[210:213], v[218:221], v[34:49]
	ds_read_b64_tr_b16 v[218:219], v151 offset:0x1600
	ds_read_b64_tr_b16 v[220:221], v151 offset:0x1e00
	s_waitcnt lgkmcnt(6)
	v_mfma_f32_32x32x16_bf16 v[34:49], v[152:155], v[222:225], v[34:49]
	ds_read_b64_tr_b16 v[222:223], v151 offset:0x2600
	ds_read_b64_tr_b16 v[224:225], v151 offset:0x2e00
	s_waitcnt lgkmcnt(6)
	v_mfma_f32_32x32x16_bf16 v[34:49], v[156:159], v[226:229], v[34:49]
	ds_read_b64_tr_b16 v[226:227], v151 offset:0x3600
	ds_read_b64_tr_b16 v[228:229], v151 offset:0x3e00
	s_waitcnt lgkmcnt(6)
	v_mfma_f32_32x32x16_bf16 v[18:33], v[146:149], v[214:217], v[18:33]
	v_max_f32_e32 v146, v82, v83
	v_max3_f32 v146, v146, v84, v85
	v_max3_f32 v146, v146, v86, v87
	v_max3_f32 v146, v146, v88, v89
	v_max3_f32 v146, v146, v90, v91
	v_max3_f32 v146, v146, v92, v93
	v_max3_f32 v146, v146, v94, v95
	v_max3_f32 v146, v146, v96, v97
	v_max3_f32 v146, v146, v66, v67
	s_waitcnt lgkmcnt(4)
	v_mfma_f32_32x32x16_bf16 v[18:33], v[210:213], v[218:221], v[18:33]
	v_max3_f32 v146, v146, v68, v69
	v_max3_f32 v146, v146, v70, v71
	v_max3_f32 v146, v146, v72, v73
	v_max3_f32 v146, v146, v74, v75
	v_max3_f32 v146, v146, v76, v77
	v_max3_f32 v146, v146, v78, v79
	v_max3_f32 v146, v146, v80, v81
	v_mov_b32_e32 v147, v146
	s_waitcnt lgkmcnt(2)
	v_mfma_f32_32x32x16_bf16 v[18:33], v[152:155], v[222:225], v[18:33]
	s_nop 0
	v_permlane32_swap_b32_e32 v146, v147
	v_max_f32_e32 v146, v146, v147
	v_sub_f32_e32 v147, v146, v150
	v_cmp_ge_f32_e32 vcc, s25, v147
	v_max_f32_e32 v146, v150, v146
	v_sub_f32_e32 v147, v150, v146
	s_cmp_eq_u64 vcc, exec
	v_mul_f32_e32 v147, 0x3e0293ee, v147
	s_waitcnt lgkmcnt(0)
	v_mfma_f32_32x32x16_bf16 v[18:33], v[156:159], v[226:229], v[18:33]
	s_cselect_b64 s[42:43], -1, 0
	v_exp_f32_e32 v147, v147
	s_add_i32 s7, s9, 0x4000
	s_cmp_lg_u32 s6, 2
	s_cselect_b32 s6, s7, 0
	s_add_i32 s10, s6, 0
	v_cndmask_b32_e64 v196, v147, 1.0, s[42:43]
	v_cmp_gt_f32_e32 vcc, 1.0, v196
	s_cbranch_vccz .LBB0_264
	s_and_saveexec_b64 s[6:7], s[38:39]
	ds_write_b32 v190, v196 offset:128
	s_or_b64 exec, exec, s[6:7]
	s_waitcnt lgkmcnt(0)
	v_add_u32_e32 v147, v173, v181
	ds_read_b128 v[152:155], v147 offset:224
	ds_read_b128 v[156:159], v147 offset:192
	ds_read_b128 v[210:213], v147 offset:160
	ds_read_b128 v[214:217], v147 offset:128
	s_waitcnt lgkmcnt(3)
	v_pk_mul_f32 v[14:15], v[14:15], v[152:153]
	s_waitcnt lgkmcnt(2)
	v_pk_mul_f32 v[10:11], v[10:11], v[156:157]
	s_waitcnt lgkmcnt(1)
	v_pk_mul_f32 v[6:7], v[6:7], v[210:211]
	v_pk_mul_f32 v[16:17], v[16:17], v[154:155]
	v_pk_mul_f32 v[12:13], v[12:13], v[158:159]
	v_pk_mul_f32 v[8:9], v[8:9], v[212:213]
	s_waitcnt lgkmcnt(0)
	v_pk_mul_f32 v[4:5], v[4:5], v[216:217]
	v_pk_mul_f32 v[2:3], v[2:3], v[214:215]
	v_pk_mul_f32 v[62:63], v[62:63], v[152:153]
	v_pk_mul_f32 v[58:59], v[58:59], v[156:157]
	v_pk_mul_f32 v[54:55], v[54:55], v[210:211]
	v_pk_mul_f32 v[64:65], v[64:65], v[154:155]
	v_pk_mul_f32 v[60:61], v[60:61], v[158:159]
	v_pk_mul_f32 v[56:57], v[56:57], v[212:213]
	v_pk_mul_f32 v[52:53], v[52:53], v[216:217]
	v_pk_mul_f32 v[50:51], v[50:51], v[214:215]
	v_pk_mul_f32 v[46:47], v[46:47], v[152:153]
	v_pk_mul_f32 v[42:43], v[42:43], v[156:157]
	v_pk_mul_f32 v[38:39], v[38:39], v[210:211]
	v_pk_mul_f32 v[48:49], v[48:49], v[154:155]
	v_pk_mul_f32 v[44:45], v[44:45], v[158:159]
	v_pk_mul_f32 v[40:41], v[40:41], v[212:213]
	v_pk_mul_f32 v[36:37], v[36:37], v[216:217]
	v_pk_mul_f32 v[34:35], v[34:35], v[214:215]
	v_pk_mul_f32 v[30:31], v[30:31], v[152:153]
	v_pk_mul_f32 v[26:27], v[26:27], v[156:157]
	v_pk_mul_f32 v[22:23], v[22:23], v[210:211]
	v_pk_mul_f32 v[32:33], v[32:33], v[154:155]
	v_pk_mul_f32 v[28:29], v[28:29], v[158:159]
	v_pk_mul_f32 v[24:25], v[24:25], v[212:213]
	v_pk_mul_f32 v[20:21], v[20:21], v[216:217]
	v_pk_mul_f32 v[18:19], v[18:19], v[214:215]
; #define RESC(a) do { if (__any((a) < 1.f)) { if (hi == 0) al_l[r32] = (a); asm volatile("s_waitcnt lgkmcnt(0)" ::: "memory"); \
;     _Pragma("unroll") for (int d = 0; d < 4; ++d) _Pragma("unroll") for (int r = 0; r < 16; ++r) o[d][r] *= al_l[crow(r, hi)]; } } while (0)
; __device__ __forceinline__ void partialSM(f32x16& p0, f32x16& p1, float& m_reg, float& mn, float& alpha) {
;     ...
;   else { mn = fmaxf(m_reg, pmax); alpha = __builtin_amdgcn_exp2f((m_reg - mn) * C); m_reg = mn; }
;   float mnC = -mn * C;
; #pragma unroll
;   for (int r = 0; r < 16; ++r) p0[r] = fmaf(p0[r], C, mnC);
; #pragma unroll
;   for (int r = 0; r < 16; ++r) p1[r] = fmaf(p1[r], C, mnC);
; #pragma unroll
;   for (int r = 0; r < 16; ++r) p0[r] = __builtin_amdgcn_exp2f(p0[r]);
; template <bool META>
; __device__ __forceinline__ void attn_unit(const bf16_t* Q, bf16_t* Oo, const bf16_t* __restrict__ Kb, const bf16_t* __restrict__ Vb, int b, int kvh, int h, int qb, char* lds, const int tid, const float* qn, const float* RT) {
;     ...
;     RESC(alB); __syncthreads();
.LBB0_264:
	v_cndmask_b32_e64 v209, v146, v150, s[42:43]
	v_mul_f32_e32 v154, 0xbe0293ee, v209
	s_add_i32 s4, s4, 2
	v_fmamk_f32 v82, v82, 0x3e0293ee, v154
	v_fmamk_f32 v83, v83, 0x3e0293ee, v154
	v_fmamk_f32 v84, v84, 0x3e0293ee, v154
	v_fmamk_f32 v85, v85, 0x3e0293ee, v154
	v_fmamk_f32 v86, v86, 0x3e0293ee, v154
	v_fmamk_f32 v87, v87, 0x3e0293ee, v154
	v_fmamk_f32 v88, v88, 0x3e0293ee, v154
	v_fmamk_f32 v89, v89, 0x3e0293ee, v154
	v_fmamk_f32 v90, v90, 0x3e0293ee, v154
	v_fmamk_f32 v91, v91, 0x3e0293ee, v154
	v_fmamk_f32 v92, v92, 0x3e0293ee, v154
	v_fmamk_f32 v93, v93, 0x3e0293ee, v154
	v_fmamk_f32 v94, v94, 0x3e0293ee, v154
	v_fmamk_f32 v95, v95, 0x3e0293ee, v154
	v_fmamk_f32 v96, v96, 0x3e0293ee, v154
	v_fmamk_f32 v97, v97, 0x3e0293ee, v154
	v_fmamk_f32 v155, v66, 0x3e0293ee, v154
	v_fmamk_f32 v156, v67, 0x3e0293ee, v154
	v_fmamk_f32 v157, v68, 0x3e0293ee, v154
	v_fmamk_f32 v158, v69, 0x3e0293ee, v154
	v_fmamk_f32 v159, v70, 0x3e0293ee, v154
	v_fmamk_f32 v160, v71, 0x3e0293ee, v154
	v_fmamk_f32 v161, v72, 0x3e0293ee, v154
	v_fmamk_f32 v198, v73, 0x3e0293ee, v154
	v_fmamk_f32 v199, v74, 0x3e0293ee, v154
	v_fmamk_f32 v200, v75, 0x3e0293ee, v154
	v_fmamk_f32 v201, v76, 0x3e0293ee, v154
	v_fmamk_f32 v202, v77, 0x3e0293ee, v154
	v_fmamk_f32 v203, v78, 0x3e0293ee, v154
	v_fmamk_f32 v204, v79, 0x3e0293ee, v154
	v_fmamk_f32 v205, v80, 0x3e0293ee, v154
	v_fmac_f32_e32 v154, 0x3e0293ee, v81
	v_exp_f32_e32 v206, v82
	v_exp_f32_e32 v207, v83
	v_exp_f32_e32 v212, v84
	v_exp_f32_e32 v213, v85
	v_exp_f32_e32 v214, v86
	v_exp_f32_e32 v215, v87
	v_exp_f32_e32 v216, v88
	v_exp_f32_e32 v217, v89
	v_exp_f32_e32 v218, v90
	v_exp_f32_e32 v219, v91
	v_exp_f32_e32 v220, v92
	v_exp_f32_e32 v221, v93
	v_exp_f32_e32 v222, v94
	v_exp_f32_e32 v223, v95
	v_exp_f32_e32 v224, v96
	v_exp_f32_e32 v225, v97
	s_waitcnt vmcnt(0)
	s_waitcnt lgkmcnt(0)
	s_barrier
; #define SLOAD(i, t) do { const long rb_ = TROW(t); const char* vt_ = (const char*)Vh + rb_ * (LDK * 2); const char* kt_ = (const char*)Kh + rb_ * (LDK * 2); \
;     sr_[i].vs0 = *(const bf16x8*)(vt_ + lo0); sr_[i].vs1 = *(const bf16x8*)(vt_ + lo0 + 32 * LDK * 2); \
;     sr_[i].ks0 = *(const bf16x8*)(kt_ + lo0); sr_[i].ks1 = *(const bf16x8*)(kt_ + lo0 + 32 * LDK * 2); } while (0)
; __device__ __forceinline__ void finishSM(f32x16& p0, f32x16& p1, float alpha, float& l_reg, bf16x8& pa0, bf16x8& pa1, bf16x8& pa2, bf16x8& pa3) {
; #pragma unroll
;   for (int r = 0; r < 16; ++r) p1[r] = __builtin_amdgcn_exp2f(p1[r]);
;   float ps = 0;
; #pragma unroll
;   for (int r = 0; r < 16; ++r) ps += p0[r];
; #pragma unroll
;   for (int r = 0; r < 16; ++r) ps += p1[r];
;   { auto rr = __builtin_amdgcn_permlane32_swap(__float_as_uint(ps), __float_as_uint(ps), false, false);
;     ps = __uint_as_float(rr[0]) + __uint_as_float(rr[1]); }
;   l_reg = l_reg * alpha + ps;
;     ...
;   PK4(p0, 0, pa0); PK4(p0, 8, pa1); PK4(p1, 0, pa2); PK4(p1, 8, pa3);
; __device__ __forceinline__ void qkt(f32x16& p0, f32x16& p1, const bf16_t* Ks, const bf16x8* qr, int r32, int hi) {
;   p0 = f32x16{}; p1 = f32x16{};
; #pragma unroll
;   for (int d0 = 0; d0 < 8; ++d0) { int cb = (d0 * 16 + hi * 8) * 2;
;     bf16x8 b0 = *reinterpret_cast<const bf16x8*>((const char*)Ks + KSWZ(r32, cb));
;     bf16x8 b1 = *reinterpret_cast<const bf16x8*>((const char*)Ks + KSWZ(32 + r32, cb));
;     p0 = __builtin_amdgcn_mfma_f32_32x32x16_bf16(b0, qr[d0], p0, 0, 0, 0);
;     p1 = __builtin_amdgcn_mfma_f32_32x32x16_bf16(b1, qr[d0], p1, 0, 0, 0); }
; }
; template <bool META>
; __device__ __forceinline__ void attn_unit(const bf16_t* Q, bf16_t* Oo, const bf16_t* __restrict__ Kb, const bf16_t* __restrict__ Vb, int b, int kvh, int h, int qb, char* lds, const int tid, const float* qn, const float* RT) {
;     ...
;     if (j + 2 < NT) SLOAD(SE, j + 2);
	v_add_u32_e32 v211, s10, v182
	ds_read_b128 v[66:69], v211 offset:49152
	ds_read_b128 v[82:85], v211 offset:50176
	ds_read_b128 v[146:149], v211 offset:51200
	ds_read_b128 v[150:153], v211 offset:52224
	v_exp_f32_e32 v155, v155
	s_waitcnt lgkmcnt(3)
	v_mfma_f32_32x32x16_bf16 v[66:81], v[66:69], v[98:101], 0
	v_exp_f32_e32 v156, v156
	v_exp_f32_e32 v157, v157
	v_exp_f32_e32 v158, v158
	v_exp_f32_e32 v159, v159
	v_exp_f32_e32 v160, v160
	v_exp_f32_e32 v161, v161
	v_exp_f32_e32 v198, v198
	s_waitcnt lgkmcnt(2)
	v_mfma_f32_32x32x16_bf16 v[82:97], v[82:85], v[98:101], 0
	v_exp_f32_e32 v199, v199
	v_exp_f32_e32 v200, v200
	v_exp_f32_e32 v201, v201
	v_exp_f32_e32 v202, v202
	v_exp_f32_e32 v203, v203
	v_exp_f32_e32 v204, v204
	v_exp_f32_e32 v205, v205
	s_waitcnt lgkmcnt(1)
	v_mfma_f32_32x32x16_bf16 v[66:81], v[146:149], v[102:105], v[66:81]
	v_exp_f32_e32 v226, v154
	v_cvt_pk_bf16_f32 v154, v155, v156
	s_waitcnt lgkmcnt(0)
	v_mfma_f32_32x32x16_bf16 v[82:97], v[150:153], v[102:105], v[82:97]
	ds_read_b128 v[146:149], v211 offset:53248
	ds_read_b128 v[150:153], v211 offset:54272
	s_waitcnt lgkmcnt(1)
	v_mfma_f32_32x32x16_bf16 v[66:81], v[146:149], v[106:109], v[66:81]
	s_waitcnt lgkmcnt(0)
	v_mfma_f32_32x32x16_bf16 v[82:97], v[150:153], v[106:109], v[82:97]
	ds_read_b128 v[146:149], v211 offset:55296
	ds_read_b128 v[150:153], v211 offset:56320
	s_waitcnt lgkmcnt(1)
	v_mfma_f32_32x32x16_bf16 v[66:81], v[146:149], v[110:113], v[66:81]
	s_waitcnt lgkmcnt(0)
	v_mfma_f32_32x32x16_bf16 v[82:97], v[150:153], v[110:113], v[82:97]
	ds_read_b128 v[146:149], v211 offset:57344
	ds_read_b128 v[150:153], v211 offset:58368
	s_waitcnt lgkmcnt(1)
	v_mfma_f32_32x32x16_bf16 v[66:81], v[146:149], v[114:117], v[66:81]
	s_waitcnt lgkmcnt(0)
	v_mfma_f32_32x32x16_bf16 v[82:97], v[150:153], v[114:117], v[82:97]
	ds_read_b128 v[146:149], v211 offset:59392
	ds_read_b128 v[150:153], v211 offset:60416
	s_waitcnt lgkmcnt(1)
	v_mfma_f32_32x32x16_bf16 v[66:81], v[146:149], v[118:121], v[66:81]
	s_waitcnt lgkmcnt(0)
	v_mfma_f32_32x32x16_bf16 v[82:97], v[150:153], v[118:121], v[82:97]
	ds_read_b128 v[146:149], v211 offset:61440
	ds_read_b128 v[150:153], v211 offset:62464
	s_waitcnt lgkmcnt(1)
	v_mfma_f32_32x32x16_bf16 v[66:81], v[146:149], v[122:125], v[66:81]
	s_waitcnt lgkmcnt(0)
	v_mfma_f32_32x32x16_bf16 v[82:97], v[150:153], v[122:125], v[82:97]
	ds_read_b128 v[146:149], v211 offset:63488
	ds_read_b128 v[150:153], v211 offset:64512
	s_waitcnt lgkmcnt(1)
	v_mfma_f32_32x32x16_bf16 v[66:81], v[146:149], v[126:129], v[66:81]
	v_add_f32_e32 v146, v207, v206
	v_add_f32_e32 v146, v212, v146
	v_add_f32_e32 v146, v213, v146
	v_add_f32_e32 v146, v214, v146
	v_add_f32_e32 v146, v215, v146
	v_add_f32_e32 v146, v216, v146
	v_add_f32_e32 v146, v217, v146
	v_add_f32_e32 v146, v218, v146
	v_add_f32_e32 v146, v219, v146
	v_add_f32_e32 v146, v220, v146
	v_add_f32_e32 v146, v221, v146
	v_add_f32_e32 v146, v222, v146
	v_add_f32_e32 v146, v223, v146
	v_add_f32_e32 v146, v224, v146
	v_add_f32_e32 v146, v225, v146
	v_add_f32_e32 v146, v155, v146
	v_add_f32_e32 v146, v156, v146
	v_add_f32_e32 v146, v157, v146
	v_add_f32_e32 v146, v158, v146
	v_add_f32_e32 v146, v159, v146
	v_add_f32_e32 v146, v160, v146
	v_add_f32_e32 v146, v161, v146
	v_add_f32_e32 v146, v198, v146
	v_add_f32_e32 v146, v199, v146
	v_add_f32_e32 v146, v200, v146
	s_waitcnt lgkmcnt(0)
	v_mfma_f32_32x32x16_bf16 v[82:97], v[150:153], v[126:129], v[82:97]
	v_add_f32_e32 v146, v201, v146
	v_add_f32_e32 v146, v202, v146
	v_add_f32_e32 v146, v203, v146
	v_add_f32_e32 v146, v204, v146
	v_add_f32_e32 v146, v205, v146
	v_add_f32_e32 v210, v226, v146
	v_mov_b32_e32 v211, v210
	v_cvt_pk_bf16_f32 v146, v206, v207
	v_cvt_pk_bf16_f32 v147, v212, v213
	v_cvt_pk_bf16_f32 v148, v214, v215
	v_cvt_pk_bf16_f32 v149, v216, v217
	v_cvt_pk_bf16_f32 v150, v218, v219
	v_cvt_pk_bf16_f32 v151, v220, v221
	v_cvt_pk_bf16_f32 v152, v222, v223
	v_cvt_pk_bf16_f32 v153, v224, v225
	v_cvt_pk_bf16_f32 v155, v157, v158
	v_cvt_pk_bf16_f32 v156, v159, v160
	v_cvt_pk_bf16_f32 v157, v161, v198
	v_cvt_pk_bf16_f32 v158, v199, v200
	v_cvt_pk_bf16_f32 v159, v201, v202
	v_cvt_pk_bf16_f32 v160, v203, v204
	v_cvt_pk_bf16_f32 v161, v205, v226
	v_permlane32_swap_b32_e32 v210, v211
	v_permlane32_swap_b32_e32 v146, v148
	v_permlane32_swap_b32_e32 v147, v149
	v_permlane32_swap_b32_e32 v150, v152
	v_permlane32_swap_b32_e32 v151, v153
	v_permlane32_swap_b32_e32 v154, v156
	v_permlane32_swap_b32_e32 v155, v157
	v_permlane32_swap_b32_e32 v158, v160
	v_permlane32_swap_b32_e32 v159, v161
	s_andn2_b64 vcc, exec, s[0:1]
	s_cbranch_vccnz .LBB0_266
	s_add_u32 s0, s90, 64
	s_addc_u32 s1, s91, 0
	s_cmpk_lt_u32 s4, 0xfe
	s_cselect_b32 s1, s1, s44
	s_cselect_b32 s0, s0, s31
	s_lshl_b64 s[0:1], s[0:1], 9
	s_add_i32 s19, s8, s18
	s_add_u32 s16, s12, s0
	s_addc_u32 s17, s13, s1
	s_mov_b32 m0, s19
	s_nop 0
	global_load_lds_dwordx4 v187, s[16:17]
	s_add_i32 m0, s19, 0x380
	s_nop 0
	global_load_lds_dwordx4 v187, s[16:17] offset:128
	s_add_u32 s16, s14, s0
	s_addc_u32 s17, s15, s1
	s_add_i32 m0, s19, 0xc000
	s_nop 0
	global_load_lds_dwordx4 v188, s[16:17]
	s_add_u32 s16, s16, 0x4000
	s_addc_u32 s17, s17, 0
	s_add_i32 m0, s19, 0xc400
	s_nop 0
	global_load_lds_dwordx4 v188, s[16:17]

; #define SBAR() __builtin_amdgcn_sched_barrier(0)
; __device__ __forceinline__ void partialSM(f32x16& p0, f32x16& p1, float& m_reg, float& mn, float& alpha) {
;   constexpr float C = ASCALE * 1.4426950408889634f;
;   float pmax = p0[0];
; #pragma unroll
;   for (int r = 1; r < 16; ++r) pmax = fmaxf(pmax, p0[r]);
; #pragma unroll
;   for (int r = 0; r < 16; ++r) pmax = fmaxf(pmax, p1[r]);
;   { auto rr = __builtin_amdgcn_permlane32_swap(__float_as_uint(pmax), __float_as_uint(pmax), false, false);
;     pmax = fmaxf(__uint_as_float(rr[0]), __uint_as_float(rr[1])); }
;   if (__builtin_expect(__all(pmax - m_reg <= ATHR / ASCALE), 1)) { mn = m_reg; alpha = 1.f; }
;   else { mn = fmaxf(m_reg, pmax); alpha = __builtin_amdgcn_exp2f((m_reg - mn) * C); m_reg = mn; }
; template <int D0> __device__ __forceinline__ void pv_one(f32x16& od, int vb, bf16x8 pa0, bf16x8 pa1, bf16x8 pa2, bf16x8 pa3) {
;   const s16x4 l0 = tr_read<v_rd_off(D0, 0, 0)>(vb), h0 = tr_read<v_rd_off(D0, 0, 1)>(vb), l1 = tr_read<v_rd_off(D0, 1, 0)>(vb), h1 = tr_read<v_rd_off(D0, 1, 1)>(vb);
;   const s16x4 l2 = tr_read<v_rd_off(D0, 2, 0)>(vb), h2 = tr_read<v_rd_off(D0, 2, 1)>(vb), l3 = tr_read<v_rd_off(D0, 3, 0)>(vb), h3 = tr_read<v_rd_off(D0, 3, 1)>(vb);
;   asm volatile("s_waitcnt lgkmcnt(0)" ::: "memory"); SBAR();
;     ...
;   od = __builtin_amdgcn_mfma_f32_32x32x16_bf16(pa0, PK(l0, h0), od, 0, 0, 0);
;   od = __builtin_amdgcn_mfma_f32_32x32x16_bf16(pa1, PK(l1, h1), od, 0, 0, 0);
;   od = __builtin_amdgcn_mfma_f32_32x32x16_bf16(pa2, PK(l2, h2), od, 0, 0, 0);
;   od = __builtin_amdgcn_mfma_f32_32x32x16_bf16(pa3, PK(l3, h3), od, 0, 0, 0);
;     ...
; }
; __device__ __forceinline__ void pv_d0(f32x16* o, int vb, bf16x8 pa0, bf16x8 pa1, bf16x8 pa2, bf16x8 pa3) {
;   pv_one<0>(o[0], vb, pa0, pa1, pa2, pa3); pv_one<1>(o[1], vb, pa0, pa1, pa2, pa3); pv_one<2>(o[2], vb, pa0, pa1, pa2, pa3); pv_one<3>(o[3], vb, pa0, pa1, pa2, pa3);
.Latt_nomask:
	v_add_u32_e32 v198, s9, v178
	ds_read_b64_tr_b16 v[212:213], v198 offset:0
	ds_read_b64_tr_b16 v[214:215], v198 offset:0x800
	ds_read_b64_tr_b16 v[216:217], v198 offset:0x1000
	ds_read_b64_tr_b16 v[218:219], v198 offset:0x1800
	ds_read_b64_tr_b16 v[220:221], v198 offset:0x2000
	ds_read_b64_tr_b16 v[222:223], v198 offset:0x2800
	ds_read_b64_tr_b16 v[224:225], v198 offset:0x3000
	ds_read_b64_tr_b16 v[226:227], v198 offset:0x3800
	s_waitcnt lgkmcnt(6)
	s_nop 0
	v_mfma_f32_32x32x16_bf16 v[2:17], v[146:149], v[212:215], v[2:17]
	ds_read_b64_tr_b16 v[212:213], v198 offset:0x200
	ds_read_b64_tr_b16 v[214:215], v198 offset:0xa00
	s_waitcnt lgkmcnt(6)
	v_mfma_f32_32x32x16_bf16 v[2:17], v[150:153], v[216:219], v[2:17]
	ds_read_b64_tr_b16 v[216:217], v198 offset:0x1200
	ds_read_b64_tr_b16 v[218:219], v198 offset:0x1a00
	s_waitcnt lgkmcnt(6)
	v_mfma_f32_32x32x16_bf16 v[2:17], v[154:157], v[220:223], v[2:17]
	ds_read_b64_tr_b16 v[220:221], v198 offset:0x2200
	ds_read_b64_tr_b16 v[222:223], v198 offset:0x2a00
	s_waitcnt lgkmcnt(6)
	v_mfma_f32_32x32x16_bf16 v[2:17], v[158:161], v[224:227], v[2:17]
	ds_read_b64_tr_b16 v[224:225], v198 offset:0x3200
	ds_read_b64_tr_b16 v[226:227], v198 offset:0x3a00
	s_waitcnt lgkmcnt(6)
	v_mfma_f32_32x32x16_bf16 v[50:65], v[146:149], v[212:215], v[50:65]
	ds_read_b64_tr_b16 v[212:213], v198 offset:0x400
	ds_read_b64_tr_b16 v[214:215], v198 offset:0xc00
	s_waitcnt lgkmcnt(6)
	v_mfma_f32_32x32x16_bf16 v[50:65], v[150:153], v[216:219], v[50:65]
	ds_read_b64_tr_b16 v[216:217], v198 offset:0x1400
	ds_read_b64_tr_b16 v[218:219], v198 offset:0x1c00
	s_waitcnt lgkmcnt(6)
	v_mfma_f32_32x32x16_bf16 v[50:65], v[154:157], v[220:223], v[50:65]
	ds_read_b64_tr_b16 v[220:221], v198 offset:0x2400
	ds_read_b64_tr_b16 v[222:223], v198 offset:0x2c00
	s_waitcnt lgkmcnt(6)
	v_mfma_f32_32x32x16_bf16 v[50:65], v[158:161], v[224:227], v[50:65]
	ds_read_b64_tr_b16 v[224:225], v198 offset:0x3400
	ds_read_b64_tr_b16 v[226:227], v198 offset:0x3c00
	s_waitcnt lgkmcnt(6)
	v_mfma_f32_32x32x16_bf16 v[34:49], v[146:149], v[212:215], v[34:49]
	ds_read_b64_tr_b16 v[212:213], v198 offset:0x600
	ds_read_b64_tr_b16 v[214:215], v198 offset:0xe00
	s_waitcnt lgkmcnt(6)
	v_mfma_f32_32x32x16_bf16 v[34:49], v[150:153], v[216:219], v[34:49]
	ds_read_b64_tr_b16 v[216:217], v198 offset:0x1600
	ds_read_b64_tr_b16 v[218:219], v198 offset:0x1e00
	s_waitcnt lgkmcnt(6)
	v_mfma_f32_32x32x16_bf16 v[34:49], v[154:157], v[220:223], v[34:49]
	ds_read_b64_tr_b16 v[220:221], v198 offset:0x2600
	ds_read_b64_tr_b16 v[222:223], v198 offset:0x2e00
	s_waitcnt lgkmcnt(6)
	v_mfma_f32_32x32x16_bf16 v[34:49], v[158:161], v[224:227], v[34:49]
	ds_read_b64_tr_b16 v[224:225], v198 offset:0x3600
	ds_read_b64_tr_b16 v[226:227], v198 offset:0x3e00
	s_waitcnt lgkmcnt(6)
	v_mfma_f32_32x32x16_bf16 v[18:33], v[146:149], v[212:215], v[18:33]
	v_max_f32_e32 v230, v66, v67
	v_max3_f32 v230, v230, v68, v69
	v_max3_f32 v230, v230, v70, v71
	v_max3_f32 v230, v230, v72, v73
	v_max3_f32 v230, v230, v74, v75
	v_max3_f32 v230, v230, v76, v77
	v_max3_f32 v230, v230, v78, v79
	s_waitcnt lgkmcnt(4)
	v_mfma_f32_32x32x16_bf16 v[18:33], v[150:153], v[216:219], v[18:33]
	v_max3_f32 v230, v230, v80, v81
	v_max3_f32 v230, v230, v82, v83
	v_max3_f32 v230, v230, v84, v85
	v_max3_f32 v230, v230, v86, v87
	v_max3_f32 v230, v230, v88, v89
	v_max3_f32 v230, v230, v90, v91
	v_max3_f32 v230, v230, v92, v93
	v_max3_f32 v230, v230, v94, v95
	s_waitcnt lgkmcnt(2)
	v_mfma_f32_32x32x16_bf16 v[18:33], v[154:157], v[220:223], v[18:33]
	v_max3_f32 v230, v230, v96, v97
	v_mov_b32_e32 v231, v230
	s_nop 1
	v_permlane32_swap_b32_e32 v230, v231
	v_max_f32_e32 v230, v230, v231
	v_sub_f32_e32 v231, v230, v209
	v_cmp_ge_f32_e32 vcc, s25, v231
	v_max_f32_e32 v231, v209, v230
	s_waitcnt lgkmcnt(0)
	v_mfma_f32_32x32x16_bf16 v[18:33], v[158:161], v[224:227], v[18:33]
	v_sub_f32_e32 v230, v209, v231
	v_mul_f32_e32 v230, 0x3e0293ee, v230
	s_cmp_eq_u64 vcc, exec
	v_exp_f32_e32 v230, v230
	s_cselect_b64 s[40:41], -1, 0
	s_add_i32 s0, s8, 0
	v_cndmask_b32_e64 v230, v230, 1.0, s[40:41]
	v_cmp_gt_f32_e32 vcc, 1.0, v230
	s_cbranch_vccz .LBB0_270
	s_and_saveexec_b64 s[0:1], s[38:39]
	ds_write_b32 v190, v230 offset:128
	s_or_b64 exec, exec, s[0:1]
	s_waitcnt lgkmcnt(0)
	v_add_u32_e32 v236, v173, v181
	ds_read_b128 v[232:235], v236 offset:224
	ds_read_b128 v[130:133], v236 offset:192
	ds_read_b128 v[134:137], v236 offset:160
	ds_read_b128 v[138:141], v236 offset:128
	s_waitcnt lgkmcnt(3)
	v_pk_mul_f32 v[14:15], v[14:15], v[232:233]
	s_waitcnt lgkmcnt(2)
	v_pk_mul_f32 v[10:11], v[10:11], v[130:131]
	s_waitcnt lgkmcnt(1)
	v_pk_mul_f32 v[6:7], v[6:7], v[134:135]
	v_pk_mul_f32 v[16:17], v[16:17], v[234:235]
	v_pk_mul_f32 v[12:13], v[12:13], v[132:133]
	v_pk_mul_f32 v[8:9], v[8:9], v[136:137]
	s_waitcnt lgkmcnt(0)
	v_pk_mul_f32 v[4:5], v[4:5], v[140:141]
	v_pk_mul_f32 v[2:3], v[2:3], v[138:139]
	v_pk_mul_f32 v[62:63], v[62:63], v[232:233]
	v_pk_mul_f32 v[58:59], v[58:59], v[130:131]
	v_pk_mul_f32 v[54:55], v[54:55], v[134:135]
	v_pk_mul_f32 v[64:65], v[64:65], v[234:235]
	v_pk_mul_f32 v[60:61], v[60:61], v[132:133]
	v_pk_mul_f32 v[56:57], v[56:57], v[136:137]
	v_pk_mul_f32 v[52:53], v[52:53], v[140:141]
	v_pk_mul_f32 v[50:51], v[50:51], v[138:139]
	v_pk_mul_f32 v[46:47], v[46:47], v[232:233]
	v_pk_mul_f32 v[42:43], v[42:43], v[130:131]
	v_pk_mul_f32 v[38:39], v[38:39], v[134:135]
	v_pk_mul_f32 v[48:49], v[48:49], v[234:235]
	v_pk_mul_f32 v[44:45], v[44:45], v[132:133]
	v_pk_mul_f32 v[40:41], v[40:41], v[136:137]
	v_pk_mul_f32 v[36:37], v[36:37], v[140:141]
	v_pk_mul_f32 v[34:35], v[34:35], v[138:139]
	v_pk_mul_f32 v[30:31], v[30:31], v[232:233]
	v_pk_mul_f32 v[26:27], v[26:27], v[130:131]
	v_pk_mul_f32 v[22:23], v[22:23], v[134:135]
	v_pk_mul_f32 v[32:33], v[32:33], v[234:235]
	v_pk_mul_f32 v[28:29], v[28:29], v[132:133]
	v_pk_mul_f32 v[24:25], v[24:25], v[136:137]
	v_pk_mul_f32 v[20:21], v[20:21], v[140:141]
	v_pk_mul_f32 v[18:19], v[18:19], v[138:139]
; #define SWRITE(bb, i) do { *(bf16x8*)((char*)V_lds + (bb) * SHM_V + vst0) = sr_[i].vs0;          \
;     *(bf16x8*)((char*)V_lds + (bb) * SHM_V + vst1) = sr_[i].vs1; int kc = sc * 2;               \
;     *(bf16x8*)((char*)K_lds + (bb) * SHM_K + KSWZ(sr, kc)) = sr_[i].ks0;                       \
;     *(bf16x8*)((char*)K_lds + (bb) * SHM_K + KSWZ(32 + sr, kc)) = sr_[i].ks1; } while (0)
; #define SWAIT() asm volatile("s_waitcnt vmcnt(0)" ::: "memory")
; #define RESC(a) do { if (__any((a) < 1.f)) { if (hi == 0) al_l[r32] = (a); asm volatile("s_waitcnt lgkmcnt(0)" ::: "memory"); \
;     _Pragma("unroll") for (int d = 0; d < 4; ++d) _Pragma("unroll") for (int r = 0; r < 16; ++r) o[d][r] *= al_l[crow(r, hi)]; } } while (0)
; __device__ __forceinline__ void partialSM(f32x16& p0, f32x16& p1, float& m_reg, float& mn, float& alpha) {
;     ...
;   float mnC = -mn * C;
; #pragma unroll
;   for (int r = 0; r < 16; ++r) p0[r] = fmaf(p0[r], C, mnC);
; #pragma unroll
;   for (int r = 0; r < 16; ++r) p1[r] = fmaf(p1[r], C, mnC);
; #pragma unroll
;   for (int r = 0; r < 16; ++r) p0[r] = __builtin_amdgcn_exp2f(p0[r]);
; template <bool META>
; __device__ __forceinline__ void attn_unit(const bf16_t* Q, bf16_t* Oo, const bf16_t* __restrict__ Kb, const bf16_t* __restrict__ Vb, int b, int kvh, int h, int qb, char* lds, const int tid, const float* qn, const float* RT) {
;     ...
;     pv_d0(o, vb0 + bc * (int)SHM_V, pa0, pa1, pa2, pa3); partialSM(pA0, pA1, m_reg, mnA, alA);
;     SWAIT(); SWRITE(bp, SO);
;     RESC(alA); __syncthreads();
;     bc = bp;
.LBB0_270:
	v_cndmask_b32_e64 v150, v231, v209, s[40:41]
	v_mul_f32_e32 v232, 0xbe0293ee, v150
	v_mov_b32_e32 v158, v232
	v_fmamk_f32 v66, v66, 0x3e0293ee, v232
	v_fmamk_f32 v67, v67, 0x3e0293ee, v232
	v_fmamk_f32 v68, v68, 0x3e0293ee, v232
	v_fmamk_f32 v69, v69, 0x3e0293ee, v232
	v_fmamk_f32 v70, v70, 0x3e0293ee, v232
	v_fmamk_f32 v71, v71, 0x3e0293ee, v232
	v_fmamk_f32 v72, v72, 0x3e0293ee, v232
	v_fmamk_f32 v73, v73, 0x3e0293ee, v232
	v_fmamk_f32 v231, v74, 0x3e0293ee, v232
	v_fmamk_f32 v233, v75, 0x3e0293ee, v232
	v_fmamk_f32 v234, v76, 0x3e0293ee, v232
	v_fmamk_f32 v235, v77, 0x3e0293ee, v232
	v_fmamk_f32 v236, v78, 0x3e0293ee, v232
	v_fmamk_f32 v237, v79, 0x3e0293ee, v232
	v_fmamk_f32 v156, v80, 0x3e0293ee, v232
	v_fmac_f32_e32 v158, 0x3e0293ee, v81
	v_exp_f32_e32 v146, v66
	v_exp_f32_e32 v147, v67
	v_exp_f32_e32 v148, v68
	v_exp_f32_e32 v159, v69
	v_exp_f32_e32 v160, v70
	v_exp_f32_e32 v209, v71
	v_exp_f32_e32 v149, v72
	v_exp_f32_e32 v161, v73
	v_exp_f32_e32 v151, v231
	v_exp_f32_e32 v153, v233
	v_exp_f32_e32 v154, v234
	v_exp_f32_e32 v157, v235
	v_exp_f32_e32 v152, v236
	v_exp_f32_e32 v155, v237
	v_exp_f32_e32 v156, v156
	v_exp_f32_e32 v158, v158
	v_add_f32_e32 v66, v193, v195
	s_add_u32 s90, s90, 0x80
	v_fmac_f32_e32 v66, v192, v0
	v_add_f32_e32 v0, v210, v211
	s_addc_u32 s91, s91, 0
	v_pk_fma_f32 v[144:145], v[82:83], s[36:37], v[232:233] op_sel_hi:[1,0,0]
	v_pk_fma_f32 v[142:143], v[84:85], s[36:37], v[232:233] op_sel_hi:[1,0,0]
	v_pk_fma_f32 v[140:141], v[86:87], s[36:37], v[232:233] op_sel_hi:[1,0,0]
	v_pk_fma_f32 v[138:139], v[88:89], s[36:37], v[232:233] op_sel_hi:[1,0,0]
	v_pk_fma_f32 v[136:137], v[90:91], s[36:37], v[232:233] op_sel_hi:[1,0,0]
	v_pk_fma_f32 v[134:135], v[92:93], s[36:37], v[232:233] op_sel_hi:[1,0,0]
	v_pk_fma_f32 v[132:133], v[94:95], s[36:37], v[232:233] op_sel_hi:[1,0,0]
	v_pk_fma_f32 v[130:131], v[96:97], s[36:37], v[232:233] op_sel_hi:[1,0,0]
	v_fmac_f32_e32 v0, v66, v196
	s_cmpk_gt_u32 s4, 0xfd
	s_waitcnt vmcnt(0)
	s_waitcnt lgkmcnt(0)
	s_barrier
	s_cbranch_scc1 .LBB0_272
	v_mov_b32_e32 v192, v230
	s_branch .LBB0_260
